# attention trims: row-max NaN-canonicalising v_max removed, max-growth test done with scalar mask ops, causal-mask compare/select software-pipelined over three mask registers (no nops)
# speedup vs baseline: 1.0280x; 1.0030x over previous
.LBB0_689:
	s_add_i32 s4, s21, -1
	s_min_u32 s4, s4, s43
	s_mul_hi_u32 s5, s4, 0x55555556
	s_mul_i32 s5, s5, 3
	s_sub_i32 s5, s4, s5
	s_mul_i32 s4, s4, 0x28000
	s_lshl_b32 s5, s5, 14
	s_lshl_b32 s80, s4, 1
	s_add_i32 s50, s21, -2
	s_add_i32 s53, s5, 0
	v_lshl_add_u64 v[64:65], v[146:147], 0, s[80:81]
	s_mov_b64 s[4:5], 0xf40
	s_min_u32 s51, s50, s43
	v_lshl_add_u64 v[64:65], v[64:65], 0, s[4:5]
	s_mul_hi_u32 s4, s51, 0x55555556
	s_mul_i32 s4, s4, 3
	s_sub_i32 s4, s51, s4
	s_lshl_b32 s4, s4, 14
	s_add_i32 m0, s53, s89
	s_add_i32 s52, s4, 0
	s_mul_i32 s4, s51, 0x50000
	s_mov_b32 s5, s81
	global_load_lds_dwordx4 v[64:65], off
	v_lshl_add_u64 v[64:65], v[148:149], 0, s[4:5]
	s_add_i32 s4, s52, s95
	s_add_i32 m0, s4, 0x2000
	s_sub_i32 s4, s49, 64
	global_load_lds_dwordx4 v[64:65], off
	s_cmp_le_u32 s4, s39
	s_cbranch_scc1 .LBB0_691
	v_cmp_lt_i32_e64 s[4:5], -1, v156
	v_cmp_lt_i32_e64 s[6:7], 31, v156
	v_cmp_lt_i32_e32 vcc, 0, v156
	v_cndmask_b32_e64 v48, v249, v48, s[4:5]
	v_cmp_lt_i32_e64 s[4:5], 32, v156
	v_cndmask_b32_e64 v32, v249, v32, s[6:7]
	v_cmp_lt_i32_e64 s[6:7], 1, v156
	v_cndmask_b32_e32 v49, v249, v49, vcc
	v_cmp_lt_i32_e32 vcc, 33, v156
	v_cndmask_b32_e64 v33, v249, v33, s[4:5]
	v_cmp_lt_i32_e64 s[4:5], 2, v156
	v_cndmask_b32_e64 v50, v249, v50, s[6:7]
	v_cmp_lt_i32_e64 s[6:7], 34, v156
	v_cndmask_b32_e32 v34, v249, v34, vcc
	v_cmp_lt_i32_e32 vcc, 7, v156
	v_cndmask_b32_e64 v51, v249, v51, s[4:5]
	v_cmp_lt_i32_e64 s[4:5], 39, v156
	v_cndmask_b32_e64 v35, v249, v35, s[6:7]
	v_cmp_lt_i32_e64 s[6:7], 8, v156
	v_cndmask_b32_e32 v52, v249, v52, vcc
	v_cmp_lt_i32_e32 vcc, 40, v156
	v_cndmask_b32_e64 v36, v249, v36, s[4:5]
	v_cmp_lt_i32_e64 s[4:5], 9, v156
	v_cndmask_b32_e64 v53, v249, v53, s[6:7]
	v_cmp_lt_i32_e64 s[6:7], 41, v156
	v_cndmask_b32_e32 v37, v249, v37, vcc
	v_cmp_lt_i32_e32 vcc, 10, v156
	v_cndmask_b32_e64 v54, v249, v54, s[4:5]
	v_cmp_lt_i32_e64 s[4:5], 42, v156
	v_cndmask_b32_e64 v38, v249, v38, s[6:7]
	v_cmp_lt_i32_e64 s[6:7], 15, v156
	v_cndmask_b32_e32 v55, v249, v55, vcc
	v_cmp_lt_i32_e32 vcc, 47, v156
	v_cndmask_b32_e64 v39, v249, v39, s[4:5]
	v_cmp_lt_i32_e64 s[4:5], 16, v156
	v_cndmask_b32_e64 v56, v249, v56, s[6:7]
	v_cmp_lt_i32_e64 s[6:7], 48, v156
	v_cndmask_b32_e32 v40, v249, v40, vcc
	v_cmp_lt_i32_e32 vcc, 17, v156
	v_cndmask_b32_e64 v57, v249, v57, s[4:5]
	v_cmp_lt_i32_e64 s[4:5], 49, v156
	v_cndmask_b32_e64 v41, v249, v41, s[6:7]
	v_cmp_lt_i32_e64 s[6:7], 18, v156
	v_cndmask_b32_e32 v58, v249, v58, vcc
	v_cmp_lt_i32_e32 vcc, 50, v156
	v_cndmask_b32_e64 v42, v249, v42, s[4:5]
	v_cmp_lt_i32_e64 s[4:5], 23, v156
	v_cndmask_b32_e64 v59, v249, v59, s[6:7]
	v_cmp_lt_i32_e64 s[6:7], 55, v156
	v_cndmask_b32_e32 v43, v249, v43, vcc
	v_cmp_lt_i32_e32 vcc, 24, v156
	v_cndmask_b32_e64 v60, v249, v60, s[4:5]
	v_cmp_lt_i32_e64 s[4:5], 56, v156
	v_cndmask_b32_e64 v44, v249, v44, s[6:7]
	v_cmp_lt_i32_e64 s[6:7], 25, v156
	v_cndmask_b32_e32 v61, v249, v61, vcc
	v_cmp_lt_i32_e32 vcc, 57, v156
	v_cndmask_b32_e64 v45, v249, v45, s[4:5]
	v_cmp_lt_i32_e64 s[4:5], 26, v156
	v_cndmask_b32_e64 v62, v249, v62, s[6:7]
	v_cmp_lt_i32_e64 s[6:7], 58, v156
	v_cndmask_b32_e32 v46, v249, v46, vcc
	s_nop 0
	v_cndmask_b32_e64 v63, v249, v63, s[4:5]
	s_nop 0
	v_cndmask_b32_e64 v47, v249, v47, s[6:7]
.LBB0_691:
	s_add_i32 s4, s21, -3
	s_min_u32 s54, s4, s43
	s_mul_hi_u32 s4, s54, 0x55555556
	s_mul_i32 s4, s4, 3
	s_sub_i32 s4, s54, s4
	v_lshl_add_u32 v64, s4, 14, v153
	ds_read_b128 v[140:143], v64
	ds_read_b128 v[132:135], v64 offset:512
	ds_read_b128 v[136:139], v64 offset:2048
	ds_read_b128 v[120:123], v64 offset:2560
	ds_read_b128 v[128:131], v64 offset:4096
	ds_read_b128 v[116:119], v64 offset:4608
	ds_read_b128 v[124:127], v64 offset:6144
	ds_read_b128 v[112:115], v64 offset:6656
	s_nop 0
	v_max3_f32 v64, v48, v32, v49
	v_max3_f32 v65, v33, v50, v34
	v_max3_f32 v64, v64, v51, v35
	v_max3_f32 v65, v65, v52, v36
	v_max3_f32 v64, v64, v53, v37
	v_max3_f32 v65, v65, v54, v38
	v_max3_f32 v64, v64, v55, v39
	v_max3_f32 v65, v65, v56, v40
	v_max3_f32 v64, v64, v57, v41
	v_max3_f32 v65, v65, v58, v42
	v_max3_f32 v64, v64, v59, v43
	v_max3_f32 v65, v65, v60, v44
	v_max3_f32 v64, v64, v61, v45
	v_max3_f32 v65, v65, v62, v46
	v_max3_f32 v64, v64, v63, v47
	v_max_f32_e32 v64, v64, v65
	v_mov_b32_e32 v65, v64
	s_nop 1
	v_permlane32_swap_b32_e32 v64, v65
	v_max_f32_e32 v64, v64, v65
	v_cmp_lt_f32_e32 vcc, s97, v64
	v_cmp_lg_f32_e64 s[4:5], s96, v64
	s_nop 1
	s_and_b64 s[6:7], vcc, s[2:3]
	s_andn2_b64 vcc, s[4:5], s[2:3]
	s_or_b64 s[6:7], s[6:7], vcc
	s_and_b64 vcc, s[6:7], exec
	s_cbranch_vccz .LBB0_693
	v_cndmask_b32_e64 v64, 0, v64, s[6:7]
	v_exp_f32_e64 v66, -v64
	s_or_b64 s[4:5], s[2:3], s[4:5]
	s_andn2_b64 s[2:3], s[2:3], exec
	s_and_b64 s[4:5], s[4:5], exec
	v_pk_add_f32 v[48:49], v[48:49], v[64:65] op_sel_hi:[1,0] neg_lo:[0,1] neg_hi:[0,1]
	v_pk_add_f32 v[32:33], v[32:33], v[64:65] op_sel_hi:[1,0] neg_lo:[0,1] neg_hi:[0,1]
	v_pk_add_f32 v[50:51], v[50:51], v[64:65] op_sel_hi:[1,0] neg_lo:[0,1] neg_hi:[0,1]
	v_pk_add_f32 v[34:35], v[34:35], v[64:65] op_sel_hi:[1,0] neg_lo:[0,1] neg_hi:[0,1]
	v_pk_add_f32 v[52:53], v[52:53], v[64:65] op_sel_hi:[1,0] neg_lo:[0,1] neg_hi:[0,1]
	v_pk_add_f32 v[36:37], v[36:37], v[64:65] op_sel_hi:[1,0] neg_lo:[0,1] neg_hi:[0,1]
	v_pk_add_f32 v[54:55], v[54:55], v[64:65] op_sel_hi:[1,0] neg_lo:[0,1] neg_hi:[0,1]
	v_pk_add_f32 v[38:39], v[38:39], v[64:65] op_sel_hi:[1,0] neg_lo:[0,1] neg_hi:[0,1]
	v_pk_add_f32 v[56:57], v[56:57], v[64:65] op_sel_hi:[1,0] neg_lo:[0,1] neg_hi:[0,1]
	v_pk_add_f32 v[40:41], v[40:41], v[64:65] op_sel_hi:[1,0] neg_lo:[0,1] neg_hi:[0,1]
	v_pk_add_f32 v[58:59], v[58:59], v[64:65] op_sel_hi:[1,0] neg_lo:[0,1] neg_hi:[0,1]
	v_pk_add_f32 v[42:43], v[42:43], v[64:65] op_sel_hi:[1,0] neg_lo:[0,1] neg_hi:[0,1]
	v_pk_add_f32 v[60:61], v[60:61], v[64:65] op_sel_hi:[1,0] neg_lo:[0,1] neg_hi:[0,1]
	v_pk_add_f32 v[44:45], v[44:45], v[64:65] op_sel_hi:[1,0] neg_lo:[0,1] neg_hi:[0,1]
	v_pk_add_f32 v[62:63], v[62:63], v[64:65] op_sel_hi:[1,0] neg_lo:[0,1] neg_hi:[0,1]
	v_pk_add_f32 v[46:47], v[46:47], v[64:65] op_sel_hi:[1,0] neg_lo:[0,1] neg_hi:[0,1]
	v_add_f32_e32 v154, v154, v64
	v_mul_f32_e32 v150, v150, v66
	v_pk_mul_f32 v[30:31], v[30:31], v[66:67] op_sel_hi:[1,0]
	v_pk_mul_f32 v[28:29], v[28:29], v[66:67] op_sel_hi:[1,0]
	v_pk_mul_f32 v[26:27], v[26:27], v[66:67] op_sel_hi:[1,0]
	v_pk_mul_f32 v[24:25], v[24:25], v[66:67] op_sel_hi:[1,0]
	v_pk_mul_f32 v[22:23], v[22:23], v[66:67] op_sel_hi:[1,0]
	v_pk_mul_f32 v[20:21], v[20:21], v[66:67] op_sel_hi:[1,0]
	v_pk_mul_f32 v[18:19], v[18:19], v[66:67] op_sel_hi:[1,0]
	v_pk_mul_f32 v[16:17], v[16:17], v[66:67] op_sel_hi:[1,0]
	v_pk_mul_f32 v[14:15], v[14:15], v[66:67] op_sel_hi:[1,0]
	v_pk_mul_f32 v[12:13], v[12:13], v[66:67] op_sel_hi:[1,0]
	v_pk_mul_f32 v[10:11], v[10:11], v[66:67] op_sel_hi:[1,0]
	v_pk_mul_f32 v[8:9], v[8:9], v[66:67] op_sel_hi:[1,0]
	v_pk_mul_f32 v[6:7], v[6:7], v[66:67] op_sel_hi:[1,0]
	v_pk_mul_f32 v[4:5], v[4:5], v[66:67] op_sel_hi:[1,0]
	v_pk_mul_f32 v[2:3], v[2:3], v[66:67] op_sel_hi:[1,0]
	v_pk_mul_f32 v[0:1], v[0:1], v[66:67] op_sel_hi:[1,0]
	s_or_b64 s[2:3], s[2:3], s[4:5]
.LBB0_693:
	s_mul_hi_u32 s5, s48, 0xaaaaaaab
	s_lshr_b32 s5, s5, 1
	s_add_i32 s4, s21, -4
	s_mul_i32 s5, s5, 0xffff4000
	v_lshrrev_b64 v[64:65], s54, v[144:145]
	v_and_b32_e32 v64, 1, v64
	v_cmp_eq_u32_e32 vcc, 1, v64
	v_exp_f32_e32 v48, v48
	v_exp_f32_e32 v49, v49
	v_cndmask_b32_e64 v64, v249, -v154, vcc
	v_mov_b32_e32 v65, v64
	v_mov_b32_e32 v66, v64
	v_mov_b32_e32 v67, v64
	v_mov_b32_e32 v68, v64
	v_mov_b32_e32 v69, v64
	v_mov_b32_e32 v70, v64
	v_mov_b32_e32 v71, v64
	v_mov_b32_e32 v72, v64
	v_mov_b32_e32 v73, v64
	v_mov_b32_e32 v74, v64
	v_mov_b32_e32 v75, v64
	v_mov_b32_e32 v76, v64
	v_mov_b32_e32 v77, v64
	v_mov_b32_e32 v78, v64
	v_mov_b32_e32 v79, v64
	v_exp_f32_e32 v50, v50
	v_exp_f32_e32 v51, v51
	s_waitcnt lgkmcnt(0)
	v_mfma_f32_32x32x16_bf16 v[80:95], v[140:143], v[96:99], v[64:79]
	v_add_u32_e32 v140, s5, v155
	v_exp_f32_e32 v52, v52
	v_exp_f32_e32 v53, v53
	v_exp_f32_e32 v54, v54
	v_exp_f32_e32 v55, v55
	v_exp_f32_e32 v56, v56
	v_exp_f32_e32 v57, v57
	v_mfma_f32_32x32x16_bf16 v[64:79], v[132:135], v[96:99], v[64:79]
	v_exp_f32_e32 v58, v58
	v_exp_f32_e32 v59, v59
	v_exp_f32_e32 v60, v60
	v_exp_f32_e32 v61, v61
	v_exp_f32_e32 v62, v62
	v_exp_f32_e32 v63, v63
	v_mfma_f32_32x32x16_bf16 v[80:95], v[136:139], v[100:103], v[80:95]
	ds_read_b64_tr_b16 v[132:133], v140 offset:8192
	ds_read_b64_tr_b16 v[134:135], v140 offset:8704
	ds_read_b64_tr_b16 v[136:137], v140 offset:9216
	ds_read_b64_tr_b16 v[138:139], v140 offset:9728
	v_mfma_f32_32x32x16_bf16 v[80:95], v[128:131], v[104:107], v[80:95]
	v_mfma_f32_32x32x16_bf16 v[64:79], v[120:123], v[100:103], v[64:79]
	v_mfma_f32_32x32x16_bf16 v[80:95], v[124:127], v[108:111], v[80:95]
	ds_read_b64_tr_b16 v[120:121], v140 offset:12288
	ds_read_b64_tr_b16 v[122:123], v140 offset:12800
	ds_read_b64_tr_b16 v[124:125], v140 offset:13312
	ds_read_b64_tr_b16 v[126:127], v140 offset:13824
	s_nop 1
	s_nop 0
	v_add_f32_e32 v128, v215, v48
	v_add_f32_e32 v129, v215, v49
	v_cvt_pk_bf16_f32 v130, v60, v61
	v_add_f32_e32 v128, v128, v50
	v_mfma_f32_32x32x16_bf16 v[64:79], v[116:119], v[104:107], v[64:79]
	v_add_f32_e32 v116, v129, v51
	v_add_f32_e32 v117, v128, v52
	v_cvt_pk_bf16_f32 v118, v52, v53
	v_add_f32_e32 v116, v116, v53
	v_add_f32_e32 v117, v117, v54
	v_cvt_pk_bf16_f32 v119, v54, v55
	v_add_f32_e32 v116, v116, v55
	v_add_f32_e32 v117, v117, v56
	v_cvt_pk_bf16_f32 v128, v56, v57
	v_add_f32_e32 v116, v116, v57
	v_add_f32_e32 v117, v117, v58
	v_cvt_pk_bf16_f32 v129, v58, v59
	v_add_f32_e32 v116, v116, v59
	v_add_f32_e32 v117, v117, v60
	v_cvt_pk_bf16_f32 v131, v62, v63
	v_add_f32_e32 v116, v116, v61
	v_add_f32_e32 v141, v117, v62
	v_cvt_pk_bf16_f32 v117, v50, v51
	v_add_f32_e32 v142, v116, v63
	v_cvt_pk_bf16_f32 v116, v48, v49
	s_waitcnt lgkmcnt(0)
	s_nop 0
	v_mfma_f32_32x32x16_bf16 v[0:15], v[132:135], v[116:119], v[0:15]
	v_exp_f32_e32 v32, v32
	v_exp_f32_e32 v33, v33
	v_exp_f32_e32 v34, v34
	v_exp_f32_e32 v35, v35
	v_exp_f32_e32 v36, v36
	v_exp_f32_e32 v37, v37
	v_exp_f32_e32 v38, v38
	v_mfma_f32_32x32x16_bf16 v[16:31], v[120:123], v[116:119], v[16:31]
	v_exp_f32_e32 v39, v39
	v_exp_f32_e32 v40, v40
	v_exp_f32_e32 v41, v41
	v_exp_f32_e32 v42, v42
	v_exp_f32_e32 v43, v43
	v_exp_f32_e32 v44, v44
	v_exp_f32_e32 v45, v45
	v_mfma_f32_32x32x16_bf16 v[0:15], v[136:139], v[128:131], v[0:15]
	v_exp_f32_e32 v46, v46
	v_exp_f32_e32 v47, v47
	v_mfma_f32_32x32x16_bf16 v[16:31], v[124:127], v[128:131], v[16:31]
	ds_read_b64_tr_b16 v[116:117], v140 offset:10240
	ds_read_b64_tr_b16 v[118:119], v140 offset:10752
	ds_read_b64_tr_b16 v[120:121], v140 offset:14336
	ds_read_b64_tr_b16 v[122:123], v140 offset:14848
	ds_read_b64_tr_b16 v[124:125], v140 offset:11264
	ds_read_b64_tr_b16 v[126:127], v140 offset:11776
	ds_read_b64_tr_b16 v[128:129], v140 offset:15360
	ds_read_b64_tr_b16 v[130:131], v140 offset:15872
	s_nop 1
	s_nop 0
	v_add_f32_e32 v132, v141, v32
	v_add_f32_e32 v133, v142, v33
	v_cvt_pk_bf16_f32 v134, v36, v37
	v_add_f32_e32 v132, v132, v34
	v_add_f32_e32 v133, v133, v35
	v_cvt_pk_bf16_f32 v135, v38, v39
	v_add_f32_e32 v132, v132, v36
	v_add_f32_e32 v133, v133, v37
	v_cvt_pk_bf16_f32 v136, v40, v41
	v_add_f32_e32 v132, v132, v38
	v_add_f32_e32 v133, v133, v39
	v_cvt_pk_bf16_f32 v137, v42, v43
	v_add_f32_e32 v132, v132, v40
	v_add_f32_e32 v133, v133, v41
	v_cvt_pk_bf16_f32 v138, v44, v45
	v_add_f32_e32 v132, v132, v42
	v_add_f32_e32 v133, v133, v43
	v_cvt_pk_bf16_f32 v139, v46, v47
	v_add_f32_e32 v132, v132, v44
	v_add_f32_e32 v133, v133, v45
	v_add_f32_e32 v140, v132, v46
	v_add_f32_e32 v141, v133, v47
	v_cvt_pk_bf16_f32 v132, v32, v33
	s_nop 0
	v_cvt_pk_bf16_f32 v133, v34, v35
	v_add_f32_e32 v140, v140, v141
	s_waitcnt lgkmcnt(0)
	v_mfma_f32_32x32x16_bf16 v[0:15], v[116:119], v[132:135], v[0:15]
	s_waitcnt vmcnt(2) lgkmcnt(0)
	s_barrier
	v_add_f32_e32 v150, v150, v140
	s_cmp_ge_u32 s4, s43
	v_mfma_f32_32x32x16_bf16 v[16:31], v[120:123], v[132:135], v[16:31]
	v_mfma_f32_32x32x16_bf16 v[0:15], v[124:127], v[136:139], v[0:15]
	v_mfma_f32_32x32x16_bf16 v[16:31], v[128:131], v[136:139], v[16:31]
	v_mfma_f32_32x32x16_bf16 v[64:79], v[112:115], v[108:111], v[64:79]
	s_cbranch_scc1 .LBB0_688
	s_min_u32 s4, s21, s43
	s_mul_hi_u32 s5, s4, 0x55555556
	s_mul_i32 s5, s5, 3
	s_sub_i32 s5, s4, s5
	s_lshl_b32 s6, s5, 14
	s_mul_i32 s4, s4, 0x50000
	s_mov_b32 s5, s81
	v_lshl_add_u64 v[32:33], v[146:147], 0, s[4:5]
	s_mov_b64 s[4:5], 0xf40
	v_lshl_add_u64 v[32:33], v[32:33], 0, s[4:5]
	s_add_i32 m0, s61, s6
	s_add_i32 s4, s53, s95
	global_load_lds_dwordx4 v[32:33], off
	v_lshl_add_u64 v[32:33], v[148:149], 0, s[80:81]
	s_add_i32 m0, s4, 0x2000
	s_cmp_le_u32 s49, s39
	global_load_lds_dwordx4 v[32:33], off
	s_cbranch_scc1 .LBB0_696
	v_subrev_u32_e32 v32, 64, v156
	v_cmp_lt_i32_e64 s[4:5], -1, v32
	v_cmp_lt_i32_e64 s[6:7], 31, v32
	v_cmp_lt_i32_e32 vcc, 0, v32
	v_cndmask_b32_e64 v80, v249, v80, s[4:5]
	v_cmp_lt_i32_e64 s[4:5], 32, v32
	v_cndmask_b32_e64 v64, v249, v64, s[6:7]
	v_cmp_lt_i32_e64 s[6:7], 1, v32
	v_cndmask_b32_e32 v81, v249, v81, vcc
	v_cmp_lt_i32_e32 vcc, 33, v32
	v_cndmask_b32_e64 v65, v249, v65, s[4:5]
	v_cmp_lt_i32_e64 s[4:5], 2, v32
	v_cndmask_b32_e64 v82, v249, v82, s[6:7]
	v_cmp_lt_i32_e64 s[6:7], 34, v32
	v_cndmask_b32_e32 v66, v249, v66, vcc
	v_cmp_lt_i32_e32 vcc, 7, v32
	v_cndmask_b32_e64 v83, v249, v83, s[4:5]
	v_cmp_lt_i32_e64 s[4:5], 39, v32
	v_cndmask_b32_e64 v67, v249, v67, s[6:7]
	v_cmp_lt_i32_e64 s[6:7], 8, v32
	v_cndmask_b32_e32 v84, v249, v84, vcc
	v_cmp_lt_i32_e32 vcc, 40, v32
	v_cndmask_b32_e64 v68, v249, v68, s[4:5]
	v_cmp_lt_i32_e64 s[4:5], 9, v32
	v_cndmask_b32_e64 v85, v249, v85, s[6:7]
	v_cmp_lt_i32_e64 s[6:7], 41, v32
	v_cndmask_b32_e32 v69, v249, v69, vcc
	v_cmp_lt_i32_e32 vcc, 10, v32
	v_cndmask_b32_e64 v86, v249, v86, s[4:5]
	v_cmp_lt_i32_e64 s[4:5], 42, v32
	v_cndmask_b32_e64 v70, v249, v70, s[6:7]
	v_cmp_lt_i32_e64 s[6:7], 15, v32
	v_cndmask_b32_e32 v87, v249, v87, vcc
	v_cmp_lt_i32_e32 vcc, 47, v32
	v_cndmask_b32_e64 v71, v249, v71, s[4:5]
	v_cmp_lt_i32_e64 s[4:5], 16, v32
	v_cndmask_b32_e64 v88, v249, v88, s[6:7]
	v_cmp_lt_i32_e64 s[6:7], 48, v32
	v_cndmask_b32_e32 v72, v249, v72, vcc
	v_cmp_lt_i32_e32 vcc, 17, v32
	v_cndmask_b32_e64 v89, v249, v89, s[4:5]
	v_cmp_lt_i32_e64 s[4:5], 49, v32
	v_cndmask_b32_e64 v73, v249, v73, s[6:7]
	v_cmp_lt_i32_e64 s[6:7], 18, v32
	v_cndmask_b32_e32 v90, v249, v90, vcc
	v_cmp_lt_i32_e32 vcc, 50, v32
	v_cndmask_b32_e64 v74, v249, v74, s[4:5]
	v_cmp_lt_i32_e64 s[4:5], 23, v32
	v_cndmask_b32_e64 v91, v249, v91, s[6:7]
	v_cmp_lt_i32_e64 s[6:7], 55, v32
	v_cndmask_b32_e32 v75, v249, v75, vcc
	v_cmp_lt_i32_e32 vcc, 24, v32
	v_cndmask_b32_e64 v92, v249, v92, s[4:5]
	v_cmp_lt_i32_e64 s[4:5], 56, v32
	v_cndmask_b32_e64 v76, v249, v76, s[6:7]
	v_cmp_lt_i32_e64 s[6:7], 25, v32
	v_cndmask_b32_e32 v93, v249, v93, vcc
	v_cmp_lt_i32_e32 vcc, 57, v32
	v_cndmask_b32_e64 v77, v249, v77, s[4:5]
	v_cmp_lt_i32_e64 s[4:5], 26, v32
	v_cndmask_b32_e64 v94, v249, v94, s[6:7]
	v_cmp_lt_i32_e64 s[6:7], 58, v32
	v_cndmask_b32_e32 v78, v249, v78, vcc
	s_nop 0
	v_cndmask_b32_e64 v95, v249, v95, s[4:5]
	s_nop 0
	v_cndmask_b32_e64 v79, v249, v79, s[6:7]
.LBB0_696:
	v_add3_u32 v32, s52, v151, v152
	ds_read_b128 v[140:143], v32
	ds_read_b128 v[132:135], v32 offset:512
	ds_read_b128 v[136:139], v32 offset:2048
	ds_read_b128 v[120:123], v32 offset:2560
	ds_read_b128 v[128:131], v32 offset:4096
	ds_read_b128 v[116:119], v32 offset:4608
	ds_read_b128 v[124:127], v32 offset:6144
	ds_read_b128 v[112:115], v32 offset:6656
	s_nop 0
	v_max3_f32 v32, v80, v64, v81
	v_max3_f32 v33, v65, v82, v66
	v_max3_f32 v32, v32, v83, v67
	v_max3_f32 v33, v33, v84, v68
	v_max3_f32 v32, v32, v85, v69
	v_max3_f32 v33, v33, v86, v70
	v_max3_f32 v32, v32, v87, v71
	v_max3_f32 v33, v33, v88, v72
	v_max3_f32 v32, v32, v89, v73
	v_max3_f32 v33, v33, v90, v74
	v_max3_f32 v32, v32, v91, v75
	v_max3_f32 v33, v33, v92, v76
	v_max3_f32 v32, v32, v93, v77
	v_max3_f32 v33, v33, v94, v78
	v_max3_f32 v32, v32, v95, v79
	v_max_f32_e32 v32, v32, v33
	v_mov_b32_e32 v33, v32
	s_nop 1
	v_permlane32_swap_b32_e32 v32, v33
	v_max_f32_e32 v32, v32, v33
	v_cmp_lt_f32_e32 vcc, s97, v32
	v_cmp_lg_f32_e64 s[4:5], s96, v32
	s_nop 1
	s_and_b64 s[6:7], vcc, s[2:3]
	s_andn2_b64 vcc, s[4:5], s[2:3]
	s_or_b64 s[6:7], s[6:7], vcc
	s_and_b64 vcc, s[6:7], exec
	s_cbranch_vccnz .LBB0_686
	v_xor_b32_e32 v32, 0x80000000, v154
	s_branch .LBB0_687

.LBB0_704:
	s_add_i32 s4, s18, -3
	s_min_i32 s4, s4, s43
	s_mul_hi_u32 s5, s4, 0xaaaaaaab
	s_lshr_b32 s5, s5, 1
	s_mul_i32 s5, s5, 3
	s_sub_i32 s4, s4, s5
	v_lshl_add_u32 v84, s4, 14, v168
	ds_read_b128 v[80:83], v84
	ds_read_b128 v[152:155], v84 offset:512
	ds_read_b128 v[148:151], v84 offset:2048
	ds_read_b128 v[136:139], v84 offset:2560
	ds_read_b128 v[144:147], v84 offset:4096
	ds_read_b128 v[132:135], v84 offset:4608
	ds_read_b128 v[140:143], v84 offset:6144
	ds_read_b128 v[128:131], v84 offset:6656
	s_nop 0
	v_max3_f32 v84, v48, v64, v49
	v_max3_f32 v85, v65, v50, v66
	v_max3_f32 v84, v84, v51, v67
	v_max3_f32 v85, v85, v52, v68
	v_max3_f32 v84, v84, v53, v69
	v_max3_f32 v85, v85, v54, v70
	v_max3_f32 v84, v84, v55, v71
	v_max3_f32 v85, v85, v56, v72
	v_max3_f32 v84, v84, v57, v73
	v_max3_f32 v85, v85, v58, v74
	v_max3_f32 v84, v84, v59, v75
	v_max3_f32 v85, v85, v60, v76
	v_max3_f32 v84, v84, v61, v77
	v_max3_f32 v85, v85, v62, v78
	v_max3_f32 v84, v84, v63, v79
	v_max_f32_e32 v84, v84, v85
	v_mov_b32_e32 v85, v84
	s_nop 1
	v_permlane32_swap_b32_e32 v84, v85
	v_max_f32_e32 v84, v84, v85
	v_cmp_lt_f32_e32 vcc, s97, v84
	v_cmp_lg_f32_e64 s[4:5], s96, v84
	s_nop 1
	s_and_b64 s[6:7], vcc, s[2:3]
	s_andn2_b64 vcc, s[4:5], s[2:3]
	s_or_b64 s[6:7], s[6:7], vcc
	s_and_b64 vcc, s[6:7], exec
	s_cbranch_vccz .LBB0_706
	v_cndmask_b32_e64 v32, 0, v84, s[6:7]
	v_exp_f32_e64 v34, -v32
	s_or_b64 s[4:5], s[2:3], s[4:5]
	v_add_f32_e32 v171, v171, v32
	v_pk_add_f32 v[48:49], v[48:49], v[32:33] op_sel_hi:[1,0] neg_lo:[0,1] neg_hi:[0,1]
	v_pk_add_f32 v[64:65], v[64:65], v[32:33] op_sel_hi:[1,0] neg_lo:[0,1] neg_hi:[0,1]
	v_pk_add_f32 v[50:51], v[50:51], v[32:33] op_sel_hi:[1,0] neg_lo:[0,1] neg_hi:[0,1]
	v_pk_add_f32 v[66:67], v[66:67], v[32:33] op_sel_hi:[1,0] neg_lo:[0,1] neg_hi:[0,1]
	v_pk_add_f32 v[52:53], v[52:53], v[32:33] op_sel_hi:[1,0] neg_lo:[0,1] neg_hi:[0,1]
	v_pk_add_f32 v[68:69], v[68:69], v[32:33] op_sel_hi:[1,0] neg_lo:[0,1] neg_hi:[0,1]
	v_pk_add_f32 v[54:55], v[54:55], v[32:33] op_sel_hi:[1,0] neg_lo:[0,1] neg_hi:[0,1]
	v_pk_add_f32 v[70:71], v[70:71], v[32:33] op_sel_hi:[1,0] neg_lo:[0,1] neg_hi:[0,1]
	v_pk_add_f32 v[56:57], v[56:57], v[32:33] op_sel_hi:[1,0] neg_lo:[0,1] neg_hi:[0,1]
	v_pk_add_f32 v[72:73], v[72:73], v[32:33] op_sel_hi:[1,0] neg_lo:[0,1] neg_hi:[0,1]
	v_pk_add_f32 v[58:59], v[58:59], v[32:33] op_sel_hi:[1,0] neg_lo:[0,1] neg_hi:[0,1]
	v_pk_add_f32 v[74:75], v[74:75], v[32:33] op_sel_hi:[1,0] neg_lo:[0,1] neg_hi:[0,1]
	v_pk_add_f32 v[60:61], v[60:61], v[32:33] op_sel_hi:[1,0] neg_lo:[0,1] neg_hi:[0,1]
	v_pk_add_f32 v[76:77], v[76:77], v[32:33] op_sel_hi:[1,0] neg_lo:[0,1] neg_hi:[0,1]
	v_pk_add_f32 v[62:63], v[62:63], v[32:33] op_sel_hi:[1,0] neg_lo:[0,1] neg_hi:[0,1]
	v_pk_add_f32 v[78:79], v[78:79], v[32:33] op_sel_hi:[1,0] neg_lo:[0,1] neg_hi:[0,1]
	v_xor_b32_e32 v32, 0x80000000, v171
	s_andn2_b64 s[2:3], s[2:3], exec
	s_and_b64 s[4:5], s[4:5], exec
	v_mul_f32_e32 v165, v165, v34
	v_pk_mul_f32 v[14:15], v[14:15], v[34:35] op_sel_hi:[1,0]
	v_pk_mul_f32 v[12:13], v[12:13], v[34:35] op_sel_hi:[1,0]
	v_pk_mul_f32 v[10:11], v[10:11], v[34:35] op_sel_hi:[1,0]
	v_pk_mul_f32 v[8:9], v[8:9], v[34:35] op_sel_hi:[1,0]
	v_pk_mul_f32 v[6:7], v[6:7], v[34:35] op_sel_hi:[1,0]
	v_pk_mul_f32 v[4:5], v[4:5], v[34:35] op_sel_hi:[1,0]
	v_pk_mul_f32 v[2:3], v[2:3], v[34:35] op_sel_hi:[1,0]
	v_pk_mul_f32 v[0:1], v[0:1], v[34:35] op_sel_hi:[1,0]
	v_pk_mul_f32 v[30:31], v[30:31], v[34:35] op_sel_hi:[1,0]
	v_pk_mul_f32 v[28:29], v[28:29], v[34:35] op_sel_hi:[1,0]
	v_pk_mul_f32 v[26:27], v[26:27], v[34:35] op_sel_hi:[1,0]
	v_pk_mul_f32 v[24:25], v[24:25], v[34:35] op_sel_hi:[1,0]
	v_pk_mul_f32 v[22:23], v[22:23], v[34:35] op_sel_hi:[1,0]
	v_pk_mul_f32 v[20:21], v[20:21], v[34:35] op_sel_hi:[1,0]
	v_pk_mul_f32 v[18:19], v[18:19], v[34:35] op_sel_hi:[1,0]
	v_pk_mul_f32 v[16:17], v[16:17], v[34:35] op_sel_hi:[1,0]
	v_mov_b32_e32 v33, v32
	v_mov_b32_e32 v34, v32
	v_mov_b32_e32 v35, v32
	v_mov_b32_e32 v36, v32
	v_mov_b32_e32 v37, v32
	v_mov_b32_e32 v38, v32
	v_mov_b32_e32 v39, v32
	v_mov_b32_e32 v40, v32
	v_mov_b32_e32 v41, v32
	v_mov_b32_e32 v42, v32
	v_mov_b32_e32 v43, v32
	v_mov_b32_e32 v44, v32
	v_mov_b32_e32 v45, v32
	v_mov_b32_e32 v46, v32
	v_mov_b32_e32 v47, v32
	s_or_b64 s[2:3], s[2:3], s[4:5]

.LBB0_709:
	v_add3_u32 v48, s22, v166, v167
	ds_read_b128 v[64:67], v48
	ds_read_b128 v[152:155], v48 offset:512
	ds_read_b128 v[140:143], v48 offset:2048
	ds_read_b128 v[132:135], v48 offset:2560
	ds_read_b128 v[144:147], v48 offset:4096
	ds_read_b128 v[136:139], v48 offset:4608
	ds_read_b128 v[148:151], v48 offset:6144
	ds_read_b128 v[128:131], v48 offset:6656
	s_nop 0
	v_max3_f32 v48, v96, v80, v97
	v_max3_f32 v49, v81, v98, v82
	v_max3_f32 v48, v48, v99, v83
	v_max3_f32 v49, v49, v100, v84
	v_max3_f32 v48, v48, v101, v85
	v_max3_f32 v49, v49, v102, v86
	v_max3_f32 v48, v48, v103, v87
	v_max3_f32 v49, v49, v104, v88
	v_max3_f32 v48, v48, v105, v89
	v_max3_f32 v49, v49, v106, v90
	v_max3_f32 v48, v48, v107, v91
	v_max3_f32 v49, v49, v108, v92
	v_max3_f32 v48, v48, v109, v93
	v_max3_f32 v49, v49, v110, v94
	v_max3_f32 v48, v48, v111, v95
	v_max_f32_e32 v48, v48, v49
	v_mov_b32_e32 v49, v48
	s_nop 1
	v_permlane32_swap_b32_e32 v48, v49
	v_max_f32_e32 v48, v48, v49
	v_cmp_lt_f32_e32 vcc, s97, v48
	v_cmp_lg_f32_e64 s[4:5], s96, v48
	s_nop 1
	s_and_b64 s[6:7], vcc, s[2:3]
	s_andn2_b64 vcc, s[4:5], s[2:3]
	s_or_b64 s[6:7], s[6:7], vcc
	s_and_b64 vcc, s[6:7], exec
	s_cbranch_vccz .LBB0_700
	v_cndmask_b32_e64 v32, 0, v48, s[6:7]
	v_exp_f32_e64 v34, -v32
	s_or_b64 s[4:5], s[2:3], s[4:5]
	v_add_f32_e32 v171, v171, v32
	v_pk_add_f32 v[96:97], v[96:97], v[32:33] op_sel_hi:[1,0] neg_lo:[0,1] neg_hi:[0,1]
	v_pk_add_f32 v[80:81], v[80:81], v[32:33] op_sel_hi:[1,0] neg_lo:[0,1] neg_hi:[0,1]
	v_pk_add_f32 v[98:99], v[98:99], v[32:33] op_sel_hi:[1,0] neg_lo:[0,1] neg_hi:[0,1]
	v_pk_add_f32 v[82:83], v[82:83], v[32:33] op_sel_hi:[1,0] neg_lo:[0,1] neg_hi:[0,1]
	v_pk_add_f32 v[100:101], v[100:101], v[32:33] op_sel_hi:[1,0] neg_lo:[0,1] neg_hi:[0,1]
	v_pk_add_f32 v[84:85], v[84:85], v[32:33] op_sel_hi:[1,0] neg_lo:[0,1] neg_hi:[0,1]
	v_pk_add_f32 v[102:103], v[102:103], v[32:33] op_sel_hi:[1,0] neg_lo:[0,1] neg_hi:[0,1]
	v_pk_add_f32 v[86:87], v[86:87], v[32:33] op_sel_hi:[1,0] neg_lo:[0,1] neg_hi:[0,1]
	v_pk_add_f32 v[104:105], v[104:105], v[32:33] op_sel_hi:[1,0] neg_lo:[0,1] neg_hi:[0,1]
	v_pk_add_f32 v[88:89], v[88:89], v[32:33] op_sel_hi:[1,0] neg_lo:[0,1] neg_hi:[0,1]
	v_pk_add_f32 v[106:107], v[106:107], v[32:33] op_sel_hi:[1,0] neg_lo:[0,1] neg_hi:[0,1]
	v_pk_add_f32 v[90:91], v[90:91], v[32:33] op_sel_hi:[1,0] neg_lo:[0,1] neg_hi:[0,1]
	v_pk_add_f32 v[108:109], v[108:109], v[32:33] op_sel_hi:[1,0] neg_lo:[0,1] neg_hi:[0,1]
	v_pk_add_f32 v[92:93], v[92:93], v[32:33] op_sel_hi:[1,0] neg_lo:[0,1] neg_hi:[0,1]
	v_pk_add_f32 v[110:111], v[110:111], v[32:33] op_sel_hi:[1,0] neg_lo:[0,1] neg_hi:[0,1]
	v_pk_add_f32 v[94:95], v[94:95], v[32:33] op_sel_hi:[1,0] neg_lo:[0,1] neg_hi:[0,1]
	v_xor_b32_e32 v32, 0x80000000, v171
	s_andn2_b64 s[2:3], s[2:3], exec
	s_and_b64 s[4:5], s[4:5], exec
	v_mul_f32_e32 v165, v165, v34
	v_pk_mul_f32 v[14:15], v[14:15], v[34:35] op_sel_hi:[1,0]
	v_pk_mul_f32 v[12:13], v[12:13], v[34:35] op_sel_hi:[1,0]
	v_pk_mul_f32 v[10:11], v[10:11], v[34:35] op_sel_hi:[1,0]
	v_pk_mul_f32 v[8:9], v[8:9], v[34:35] op_sel_hi:[1,0]
	v_pk_mul_f32 v[6:7], v[6:7], v[34:35] op_sel_hi:[1,0]
	v_pk_mul_f32 v[4:5], v[4:5], v[34:35] op_sel_hi:[1,0]
	v_pk_mul_f32 v[2:3], v[2:3], v[34:35] op_sel_hi:[1,0]
	v_pk_mul_f32 v[0:1], v[0:1], v[34:35] op_sel_hi:[1,0]
	v_pk_mul_f32 v[30:31], v[30:31], v[34:35] op_sel_hi:[1,0]
	v_pk_mul_f32 v[28:29], v[28:29], v[34:35] op_sel_hi:[1,0]
	v_pk_mul_f32 v[26:27], v[26:27], v[34:35] op_sel_hi:[1,0]
	v_pk_mul_f32 v[24:25], v[24:25], v[34:35] op_sel_hi:[1,0]
	v_pk_mul_f32 v[22:23], v[22:23], v[34:35] op_sel_hi:[1,0]
	v_pk_mul_f32 v[20:21], v[20:21], v[34:35] op_sel_hi:[1,0]
	v_pk_mul_f32 v[18:19], v[18:19], v[34:35] op_sel_hi:[1,0]
	v_pk_mul_f32 v[16:17], v[16:17], v[34:35] op_sel_hi:[1,0]
	v_mov_b32_e32 v33, v32
	v_mov_b32_e32 v34, v32
	v_mov_b32_e32 v35, v32
	v_mov_b32_e32 v36, v32
	v_mov_b32_e32 v37, v32
	v_mov_b32_e32 v38, v32
	v_mov_b32_e32 v39, v32
	v_mov_b32_e32 v40, v32
	v_mov_b32_e32 v41, v32
	v_mov_b32_e32 v42, v32
	v_mov_b32_e32 v43, v32
	v_mov_b32_e32 v44, v32
	v_mov_b32_e32 v45, v32
	v_mov_b32_e32 v46, v32
	v_mov_b32_e32 v47, v32
	s_or_b64 s[2:3], s[2:3], s[4:5]
	s_branch .LBB0_700

.LBB0_717:
	s_add_i32 s4, s19, -1
	s_min_u32 s44, s4, s22
	s_mul_hi_u32 s4, s44, 0x55555556
	s_mul_i32 s4, s4, 3
	s_sub_i32 s4, s44, s4
	s_mulk_i32 s4, 0x5000
	s_add_i32 s42, s19, -2
	s_add_i32 s45, s4, 0
	s_min_u32 s4, s42, s22
	s_mul_hi_u32 s5, s4, 0x55555556
	s_mul_i32 s5, s5, 3
	s_sub_i32 s5, s4, s5
	s_mul_i32 s80, s44, 0xc000
	s_mulk_i32 s5, 0x5000
	v_lshl_add_u64 v[80:81], v[184:185], 0, s[80:81]
	s_add_i32 m0, s45, s63
	s_add_i32 s43, s5, 0
	global_load_lds_dwordx4 v[80:81], off
	v_lshl_add_u64 v[80:81], v[186:187], 0, s[80:81]
	s_add_i32 m0, s45, s75
	s_lshl_b32 s80, s4, 15
	s_add_i32 s4, s43, s95
	global_load_lds_dwordx4 v[80:81], off
	v_lshl_add_u64 v[80:81], v[188:189], 0, s[80:81]
	s_add_i32 m0, s4, 0x3000
	s_sub_i32 s4, s23, 64
	global_load_lds_dwordx4 v[80:81], off
	s_cmp_le_u32 s4, s39
	s_cbranch_scc1 .LBB0_719
	v_cmp_lt_i32_e64 s[4:5], -1, v196
	v_cmp_lt_i32_e64 s[6:7], 31, v196
	v_cmp_lt_i32_e32 vcc, 0, v196
	v_cndmask_b32_e64 v48, v249, v48, s[4:5]
	v_cmp_lt_i32_e64 s[4:5], 32, v196
	v_cndmask_b32_e64 v64, v249, v64, s[6:7]
	v_cmp_lt_i32_e64 s[6:7], 1, v196
	v_cndmask_b32_e32 v49, v249, v49, vcc
	v_cmp_lt_i32_e32 vcc, 33, v196
	v_cndmask_b32_e64 v65, v249, v65, s[4:5]
	v_cmp_lt_i32_e64 s[4:5], 2, v196
	v_cndmask_b32_e64 v50, v249, v50, s[6:7]
	v_cmp_lt_i32_e64 s[6:7], 34, v196
	v_cndmask_b32_e32 v66, v249, v66, vcc
	v_cmp_lt_i32_e32 vcc, 7, v196
	v_cndmask_b32_e64 v51, v249, v51, s[4:5]
	v_cmp_lt_i32_e64 s[4:5], 39, v196
	v_cndmask_b32_e64 v67, v249, v67, s[6:7]
	v_cmp_lt_i32_e64 s[6:7], 8, v196
	v_cndmask_b32_e32 v52, v249, v52, vcc
	v_cmp_lt_i32_e32 vcc, 40, v196
	v_cndmask_b32_e64 v68, v249, v68, s[4:5]
	v_cmp_lt_i32_e64 s[4:5], 9, v196
	v_cndmask_b32_e64 v53, v249, v53, s[6:7]
	v_cmp_lt_i32_e64 s[6:7], 41, v196
	v_cndmask_b32_e32 v69, v249, v69, vcc
	v_cmp_lt_i32_e32 vcc, 10, v196
	v_cndmask_b32_e64 v54, v249, v54, s[4:5]
	v_cmp_lt_i32_e64 s[4:5], 42, v196
	v_cndmask_b32_e64 v70, v249, v70, s[6:7]
	v_cmp_lt_i32_e64 s[6:7], 15, v196
	v_cndmask_b32_e32 v55, v249, v55, vcc
	v_cmp_lt_i32_e32 vcc, 47, v196
	v_cndmask_b32_e64 v71, v249, v71, s[4:5]
	v_cmp_lt_i32_e64 s[4:5], 16, v196
	v_cndmask_b32_e64 v56, v249, v56, s[6:7]
	v_cmp_lt_i32_e64 s[6:7], 48, v196
	v_cndmask_b32_e32 v72, v249, v72, vcc
	v_cmp_lt_i32_e32 vcc, 17, v196
	v_cndmask_b32_e64 v57, v249, v57, s[4:5]
	v_cmp_lt_i32_e64 s[4:5], 49, v196
	v_cndmask_b32_e64 v73, v249, v73, s[6:7]
	v_cmp_lt_i32_e64 s[6:7], 18, v196
	v_cndmask_b32_e32 v58, v249, v58, vcc
	v_cmp_lt_i32_e32 vcc, 50, v196
	v_cndmask_b32_e64 v74, v249, v74, s[4:5]
	v_cmp_lt_i32_e64 s[4:5], 23, v196
	v_cndmask_b32_e64 v59, v249, v59, s[6:7]
	v_cmp_lt_i32_e64 s[6:7], 55, v196
	v_cndmask_b32_e32 v75, v249, v75, vcc
	v_cmp_lt_i32_e32 vcc, 24, v196
	v_cndmask_b32_e64 v60, v249, v60, s[4:5]
	v_cmp_lt_i32_e64 s[4:5], 56, v196
	v_cndmask_b32_e64 v76, v249, v76, s[6:7]
	v_cmp_lt_i32_e64 s[6:7], 25, v196
	v_cndmask_b32_e32 v61, v249, v61, vcc
	v_cmp_lt_i32_e32 vcc, 57, v196
	v_cndmask_b32_e64 v77, v249, v77, s[4:5]
	v_cmp_lt_i32_e64 s[4:5], 26, v196
	v_cndmask_b32_e64 v62, v249, v62, s[6:7]
	v_cmp_lt_i32_e64 s[6:7], 58, v196
	v_cndmask_b32_e32 v78, v249, v78, vcc
	s_nop 0
	v_cndmask_b32_e64 v63, v249, v63, s[4:5]
	s_nop 0
	v_cndmask_b32_e64 v79, v249, v79, s[6:7]
.LBB0_719:
	s_add_i32 s4, s19, -3
	s_min_u32 s4, s4, s22
	s_mul_hi_u32 s5, s4, 0x55555556
	s_mul_i32 s5, s5, 3
	s_sub_i32 s4, s4, s5
	s_mulk_i32 s4, 0x5000
	v_add_u32_e32 v84, s4, v194
	ds_read_b128 v[80:83], v84
	ds_read_b128 v[176:179], v84 offset:512
	ds_read_b128 v[168:171], v84 offset:2048
	ds_read_b128 v[152:155], v84 offset:2560
	ds_read_b128 v[172:175], v84 offset:4096
	ds_read_b128 v[148:151], v84 offset:4608
	ds_read_b128 v[164:167], v84 offset:6144
	ds_read_b128 v[144:147], v84 offset:6656
	ds_read_b128 v[160:163], v84 offset:8192
	ds_read_b128 v[140:143], v84 offset:8704
	ds_read_b128 v[156:159], v84 offset:10240
	ds_read_b128 v[136:139], v84 offset:10752
	s_nop 0
	v_max3_f32 v84, v48, v64, v49
	v_max3_f32 v85, v65, v50, v66
	v_max3_f32 v84, v84, v51, v67
	v_max3_f32 v85, v85, v52, v68
	v_max3_f32 v84, v84, v53, v69
	v_max3_f32 v85, v85, v54, v70
	v_max3_f32 v84, v84, v55, v71
	v_max3_f32 v85, v85, v56, v72
	v_max3_f32 v84, v84, v57, v73
	v_max3_f32 v85, v85, v58, v74
	v_max3_f32 v84, v84, v59, v75
	v_max3_f32 v85, v85, v60, v76
	v_max3_f32 v84, v84, v61, v77
	v_max3_f32 v85, v85, v62, v78
	v_max3_f32 v84, v84, v63, v79
	v_max_f32_e32 v84, v84, v85
	v_mov_b32_e32 v85, v84
	s_nop 1
	v_permlane32_swap_b32_e32 v84, v85
	v_max_f32_e32 v84, v84, v85
	v_cmp_lt_f32_e32 vcc, s97, v84
	v_cmp_lg_f32_e64 s[4:5], s96, v84
	s_nop 1
	s_and_b64 s[6:7], vcc, s[2:3]
	s_andn2_b64 vcc, s[4:5], s[2:3]
	s_or_b64 s[6:7], s[6:7], vcc
	s_and_b64 vcc, s[6:7], exec
	s_cbranch_vccz .LBB0_721
	v_cndmask_b32_e64 v32, 0, v84, s[6:7]
	v_exp_f32_e64 v34, -v32
	s_or_b64 s[4:5], s[2:3], s[4:5]
	v_add_f32_e32 v197, v197, v32
	v_pk_add_f32 v[48:49], v[48:49], v[32:33] op_sel_hi:[1,0] neg_lo:[0,1] neg_hi:[0,1]
	v_pk_add_f32 v[64:65], v[64:65], v[32:33] op_sel_hi:[1,0] neg_lo:[0,1] neg_hi:[0,1]
	v_pk_add_f32 v[50:51], v[50:51], v[32:33] op_sel_hi:[1,0] neg_lo:[0,1] neg_hi:[0,1]
	v_pk_add_f32 v[66:67], v[66:67], v[32:33] op_sel_hi:[1,0] neg_lo:[0,1] neg_hi:[0,1]
	v_pk_add_f32 v[52:53], v[52:53], v[32:33] op_sel_hi:[1,0] neg_lo:[0,1] neg_hi:[0,1]
	v_pk_add_f32 v[68:69], v[68:69], v[32:33] op_sel_hi:[1,0] neg_lo:[0,1] neg_hi:[0,1]
	v_pk_add_f32 v[54:55], v[54:55], v[32:33] op_sel_hi:[1,0] neg_lo:[0,1] neg_hi:[0,1]
	v_pk_add_f32 v[70:71], v[70:71], v[32:33] op_sel_hi:[1,0] neg_lo:[0,1] neg_hi:[0,1]
	v_pk_add_f32 v[56:57], v[56:57], v[32:33] op_sel_hi:[1,0] neg_lo:[0,1] neg_hi:[0,1]
	v_pk_add_f32 v[72:73], v[72:73], v[32:33] op_sel_hi:[1,0] neg_lo:[0,1] neg_hi:[0,1]
	v_pk_add_f32 v[58:59], v[58:59], v[32:33] op_sel_hi:[1,0] neg_lo:[0,1] neg_hi:[0,1]
	v_pk_add_f32 v[74:75], v[74:75], v[32:33] op_sel_hi:[1,0] neg_lo:[0,1] neg_hi:[0,1]
	v_pk_add_f32 v[60:61], v[60:61], v[32:33] op_sel_hi:[1,0] neg_lo:[0,1] neg_hi:[0,1]
	v_pk_add_f32 v[76:77], v[76:77], v[32:33] op_sel_hi:[1,0] neg_lo:[0,1] neg_hi:[0,1]
	v_pk_add_f32 v[62:63], v[62:63], v[32:33] op_sel_hi:[1,0] neg_lo:[0,1] neg_hi:[0,1]
	v_pk_add_f32 v[78:79], v[78:79], v[32:33] op_sel_hi:[1,0] neg_lo:[0,1] neg_hi:[0,1]
	v_xor_b32_e32 v32, 0x80000000, v197
	s_andn2_b64 s[2:3], s[2:3], exec
	s_and_b64 s[4:5], s[4:5], exec
	v_mul_f32_e32 v198, v198, v34
	v_pk_mul_f32 v[30:31], v[30:31], v[34:35] op_sel_hi:[1,0]
	v_pk_mul_f32 v[28:29], v[28:29], v[34:35] op_sel_hi:[1,0]
	v_pk_mul_f32 v[26:27], v[26:27], v[34:35] op_sel_hi:[1,0]
	v_pk_mul_f32 v[24:25], v[24:25], v[34:35] op_sel_hi:[1,0]
	v_pk_mul_f32 v[22:23], v[22:23], v[34:35] op_sel_hi:[1,0]
	v_pk_mul_f32 v[20:21], v[20:21], v[34:35] op_sel_hi:[1,0]
	v_pk_mul_f32 v[18:19], v[18:19], v[34:35] op_sel_hi:[1,0]
	v_pk_mul_f32 v[16:17], v[16:17], v[34:35] op_sel_hi:[1,0]
	v_pk_mul_f32 v[14:15], v[14:15], v[34:35] op_sel_hi:[1,0]
	v_pk_mul_f32 v[12:13], v[12:13], v[34:35] op_sel_hi:[1,0]
	v_pk_mul_f32 v[10:11], v[10:11], v[34:35] op_sel_hi:[1,0]
	v_pk_mul_f32 v[8:9], v[8:9], v[34:35] op_sel_hi:[1,0]
	v_pk_mul_f32 v[6:7], v[6:7], v[34:35] op_sel_hi:[1,0]
	v_pk_mul_f32 v[4:5], v[4:5], v[34:35] op_sel_hi:[1,0]
	v_pk_mul_f32 v[2:3], v[2:3], v[34:35] op_sel_hi:[1,0]
	v_pk_mul_f32 v[0:1], v[0:1], v[34:35] op_sel_hi:[1,0]
	v_mov_b32_e32 v33, v32
	v_mov_b32_e32 v34, v32
	v_mov_b32_e32 v35, v32
	v_mov_b32_e32 v36, v32
	v_mov_b32_e32 v37, v32
	v_mov_b32_e32 v38, v32
	v_mov_b32_e32 v39, v32
	v_mov_b32_e32 v40, v32
	v_mov_b32_e32 v41, v32
	v_mov_b32_e32 v42, v32
	v_mov_b32_e32 v43, v32
	v_mov_b32_e32 v44, v32
	v_mov_b32_e32 v45, v32
	v_mov_b32_e32 v46, v32
	v_mov_b32_e32 v47, v32
	s_or_b64 s[2:3], s[2:3], s[4:5]
.LBB0_721:
	s_mul_hi_u32 s5, s21, 0xaaaaaaab
	s_lshr_b32 s5, s5, 1
	s_add_i32 s4, s19, -4
	s_mul_i32 s5, s5, 0xffff1000
	s_waitcnt lgkmcnt(0)
	v_mfma_f32_32x32x16_bf16 v[96:111], v[80:83], v[112:115], v[32:47]
	v_exp_f32_e32 v48, v48
	v_exp_f32_e32 v49, v49
	v_exp_f32_e32 v50, v50
	v_exp_f32_e32 v51, v51
	v_exp_f32_e32 v52, v52
	v_exp_f32_e32 v53, v53
	v_exp_f32_e32 v54, v54
	v_mfma_f32_32x32x16_bf16 v[80:95], v[176:179], v[112:115], v[32:47]
	v_add_u32_e32 v176, s5, v195
	v_exp_f32_e32 v55, v55
	v_exp_f32_e32 v56, v56
	v_exp_f32_e32 v57, v57
	v_exp_f32_e32 v58, v58
	v_exp_f32_e32 v59, v59
	v_exp_f32_e32 v60, v60
	v_mfma_f32_32x32x16_bf16 v[96:111], v[168:171], v[116:119], v[96:111]
	v_exp_f32_e32 v61, v61
	v_exp_f32_e32 v62, v62
	v_exp_f32_e32 v63, v63
	v_mfma_f32_32x32x16_bf16 v[96:111], v[172:175], v[120:123], v[96:111]
	ds_read_b64_tr_b16 v[168:169], v176 offset:12288
	ds_read_b64_tr_b16 v[170:171], v176 offset:12800
	ds_read_b64_tr_b16 v[172:173], v176 offset:13312
	ds_read_b64_tr_b16 v[174:175], v176 offset:13824
	v_mfma_f32_32x32x16_bf16 v[80:95], v[152:155], v[116:119], v[80:95]
	v_mfma_f32_32x32x16_bf16 v[96:111], v[164:167], v[124:127], v[96:111]
	v_mfma_f32_32x32x16_bf16 v[80:95], v[148:151], v[120:123], v[80:95]
	v_mfma_f32_32x32x16_bf16 v[96:111], v[160:163], v[128:131], v[96:111]
	v_mfma_f32_32x32x16_bf16 v[80:95], v[144:147], v[124:127], v[80:95]
	v_mfma_f32_32x32x16_bf16 v[96:111], v[156:159], v[132:135], v[96:111]
	ds_read_b64_tr_b16 v[156:157], v176 offset:16384
	ds_read_b64_tr_b16 v[158:159], v176 offset:16896
	ds_read_b64_tr_b16 v[160:161], v176 offset:17408
	ds_read_b64_tr_b16 v[162:163], v176 offset:17920
	s_nop 1
	s_nop 0
	v_add_f32_e32 v164, v215, v48
	v_add_f32_e32 v165, v215, v49
	v_cvt_pk_bf16_f32 v144, v48, v49
	v_add_f32_e32 v152, v164, v50
	v_mfma_f32_32x32x16_bf16 v[80:95], v[140:143], v[128:131], v[80:95]
	v_add_f32_e32 v153, v165, v51
	v_add_f32_e32 v152, v152, v52
	v_cvt_pk_bf16_f32 v145, v50, v51
	v_add_f32_e32 v153, v153, v53
	v_add_f32_e32 v152, v152, v54
	v_cvt_pk_bf16_f32 v146, v52, v53
	v_add_f32_e32 v153, v153, v55
	v_add_f32_e32 v152, v152, v56
	v_cvt_pk_bf16_f32 v147, v54, v55
	v_add_f32_e32 v148, v153, v57
	v_add_f32_e32 v149, v152, v58
	v_cvt_pk_bf16_f32 v150, v60, v61
	v_add_f32_e32 v148, v148, v59
	v_add_f32_e32 v149, v149, v60
	v_cvt_pk_bf16_f32 v151, v62, v63
	v_add_f32_e32 v148, v148, v61
	v_add_f32_e32 v164, v149, v62
	v_cvt_pk_bf16_f32 v149, v58, v59
	v_add_f32_e32 v165, v148, v63
	v_cvt_pk_bf16_f32 v148, v56, v57
	s_waitcnt lgkmcnt(0)
	v_mfma_f32_32x32x16_bf16 v[0:15], v[168:171], v[144:147], v[0:15]
	v_exp_f32_e32 v64, v64
	v_exp_f32_e32 v65, v65
	v_exp_f32_e32 v66, v66
	v_exp_f32_e32 v67, v67
	v_exp_f32_e32 v68, v68
	v_exp_f32_e32 v69, v69
	v_exp_f32_e32 v70, v70
	v_mfma_f32_32x32x16_bf16 v[16:31], v[156:159], v[144:147], v[16:31]
	v_exp_f32_e32 v71, v71
	v_exp_f32_e32 v72, v72
	v_exp_f32_e32 v73, v73
	v_exp_f32_e32 v74, v74
	v_exp_f32_e32 v75, v75
	v_exp_f32_e32 v76, v76
	v_exp_f32_e32 v77, v77
	v_mfma_f32_32x32x16_bf16 v[0:15], v[172:175], v[148:151], v[0:15]
	v_exp_f32_e32 v78, v78
	v_exp_f32_e32 v79, v79
	v_mfma_f32_32x32x16_bf16 v[16:31], v[160:163], v[148:151], v[16:31]
	ds_read_b64_tr_b16 v[140:141], v176 offset:14336
	ds_read_b64_tr_b16 v[142:143], v176 offset:14848
	ds_read_b64_tr_b16 v[144:145], v176 offset:18432
	ds_read_b64_tr_b16 v[146:147], v176 offset:18944
	ds_read_b64_tr_b16 v[148:149], v176 offset:15360
	ds_read_b64_tr_b16 v[150:151], v176 offset:15872
	ds_read_b64_tr_b16 v[152:153], v176 offset:19456
	ds_read_b64_tr_b16 v[154:155], v176 offset:19968
	s_nop 1
	s_nop 0
	v_add_f32_e32 v156, v164, v64
	v_add_f32_e32 v157, v165, v65
	v_cvt_pk_bf16_f32 v158, v68, v69
	v_add_f32_e32 v156, v156, v66
	v_add_f32_e32 v157, v157, v67
	v_cvt_pk_bf16_f32 v159, v70, v71
	v_add_f32_e32 v156, v156, v68
	v_add_f32_e32 v157, v157, v69
	v_cvt_pk_bf16_f32 v160, v72, v73
	v_add_f32_e32 v156, v156, v70
	v_add_f32_e32 v157, v157, v71
	v_cvt_pk_bf16_f32 v161, v74, v75
	v_add_f32_e32 v156, v156, v72
	v_add_f32_e32 v157, v157, v73
	v_cvt_pk_bf16_f32 v162, v76, v77
	v_add_f32_e32 v156, v156, v74
	v_add_f32_e32 v157, v157, v75
	v_cvt_pk_bf16_f32 v163, v78, v79
	v_add_f32_e32 v156, v156, v76
	v_add_f32_e32 v157, v157, v77
	v_add_f32_e32 v164, v156, v78
	v_add_f32_e32 v165, v157, v79
	v_cvt_pk_bf16_f32 v156, v64, v65
	s_nop 0
	v_cvt_pk_bf16_f32 v157, v66, v67
	v_add_f32_e32 v164, v164, v165
	s_waitcnt lgkmcnt(0)
	v_mfma_f32_32x32x16_bf16 v[0:15], v[140:143], v[156:159], v[0:15]
	s_waitcnt vmcnt(3) lgkmcnt(0)
	s_barrier
	v_add_f32_e32 v198, v198, v164
	s_cmp_ge_u32 s4, s22
	v_mfma_f32_32x32x16_bf16 v[16:31], v[144:147], v[156:159], v[16:31]
	v_mfma_f32_32x32x16_bf16 v[0:15], v[148:151], v[160:163], v[0:15]
	v_mfma_f32_32x32x16_bf16 v[16:31], v[152:155], v[160:163], v[16:31]
	v_mfma_f32_32x32x16_bf16 v[80:95], v[136:139], v[132:135], v[80:95]
	s_cbranch_scc1 .LBB0_716
	s_min_u32 s4, s19, s22
	s_mul_hi_u32 s5, s4, 0x55555556
	s_mul_i32 s5, s5, 3
	s_sub_i32 s5, s4, s5
	s_mulk_i32 s5, 0x5000
	s_add_i32 s5, s5, 0
	s_mul_i32 s80, s4, 0xc000
	v_lshl_add_u64 v[48:49], v[184:185], 0, s[80:81]
	s_add_i32 m0, s5, s63
	s_add_i32 s4, s45, s95
	global_load_lds_dwordx4 v[48:49], off
	v_lshl_add_u64 v[48:49], v[186:187], 0, s[80:81]
	s_add_i32 m0, s5, s75
	s_lshl_b32 s80, s44, 15
	global_load_lds_dwordx4 v[48:49], off
	v_lshl_add_u64 v[48:49], v[188:189], 0, s[80:81]
	s_add_i32 m0, s4, 0x3000
	s_cmp_le_u32 s23, s39
	global_load_lds_dwordx4 v[48:49], off
	s_cbranch_scc1 .LBB0_724
	v_subrev_u32_e32 v48, 64, v196
	v_cmp_lt_i32_e64 s[4:5], -1, v48
	v_cmp_lt_i32_e64 s[6:7], 31, v48
	v_cmp_lt_i32_e32 vcc, 0, v48
	v_cndmask_b32_e64 v96, v249, v96, s[4:5]
	v_cmp_lt_i32_e64 s[4:5], 32, v48
	v_cndmask_b32_e64 v80, v249, v80, s[6:7]
	v_cmp_lt_i32_e64 s[6:7], 1, v48
	v_cndmask_b32_e32 v97, v249, v97, vcc
	v_cmp_lt_i32_e32 vcc, 33, v48
	v_cndmask_b32_e64 v81, v249, v81, s[4:5]
	v_cmp_lt_i32_e64 s[4:5], 2, v48
	v_cndmask_b32_e64 v98, v249, v98, s[6:7]
	v_cmp_lt_i32_e64 s[6:7], 34, v48
	v_cndmask_b32_e32 v82, v249, v82, vcc
	v_cmp_lt_i32_e32 vcc, 7, v48
	v_cndmask_b32_e64 v99, v249, v99, s[4:5]
	v_cmp_lt_i32_e64 s[4:5], 39, v48
	v_cndmask_b32_e64 v83, v249, v83, s[6:7]
	v_cmp_lt_i32_e64 s[6:7], 8, v48
	v_cndmask_b32_e32 v100, v249, v100, vcc
	v_cmp_lt_i32_e32 vcc, 40, v48
	v_cndmask_b32_e64 v84, v249, v84, s[4:5]
	v_cmp_lt_i32_e64 s[4:5], 9, v48
	v_cndmask_b32_e64 v101, v249, v101, s[6:7]
	v_cmp_lt_i32_e64 s[6:7], 41, v48
	v_cndmask_b32_e32 v85, v249, v85, vcc
	v_cmp_lt_i32_e32 vcc, 10, v48
	v_cndmask_b32_e64 v102, v249, v102, s[4:5]
	v_cmp_lt_i32_e64 s[4:5], 42, v48
	v_cndmask_b32_e64 v86, v249, v86, s[6:7]
	v_cmp_lt_i32_e64 s[6:7], 15, v48
	v_cndmask_b32_e32 v103, v249, v103, vcc
	v_cmp_lt_i32_e32 vcc, 47, v48
	v_cndmask_b32_e64 v87, v249, v87, s[4:5]
	v_cmp_lt_i32_e64 s[4:5], 16, v48
	v_cndmask_b32_e64 v104, v249, v104, s[6:7]
	v_cmp_lt_i32_e64 s[6:7], 48, v48
	v_cndmask_b32_e32 v88, v249, v88, vcc
	v_cmp_lt_i32_e32 vcc, 17, v48
	v_cndmask_b32_e64 v105, v249, v105, s[4:5]
	v_cmp_lt_i32_e64 s[4:5], 49, v48
	v_cndmask_b32_e64 v89, v249, v89, s[6:7]
	v_cmp_lt_i32_e64 s[6:7], 18, v48
	v_cndmask_b32_e32 v106, v249, v106, vcc
	v_cmp_lt_i32_e32 vcc, 50, v48
	v_cndmask_b32_e64 v90, v249, v90, s[4:5]
	v_cmp_lt_i32_e64 s[4:5], 23, v48
	v_cndmask_b32_e64 v107, v249, v107, s[6:7]
	v_cmp_lt_i32_e64 s[6:7], 55, v48
	v_cndmask_b32_e32 v91, v249, v91, vcc
	v_cmp_lt_i32_e32 vcc, 24, v48
	v_cndmask_b32_e64 v108, v249, v108, s[4:5]
	v_cmp_lt_i32_e64 s[4:5], 56, v48
	v_cndmask_b32_e64 v92, v249, v92, s[6:7]
	v_cmp_lt_i32_e64 s[6:7], 25, v48
	v_cndmask_b32_e32 v109, v249, v109, vcc
	v_cmp_lt_i32_e32 vcc, 57, v48
	v_cndmask_b32_e64 v93, v249, v93, s[4:5]
	v_cmp_lt_i32_e64 s[4:5], 26, v48
	v_cndmask_b32_e64 v110, v249, v110, s[6:7]
	v_cmp_lt_i32_e64 s[6:7], 58, v48
	v_cndmask_b32_e32 v94, v249, v94, vcc
	s_nop 0
	v_cndmask_b32_e64 v111, v249, v111, s[4:5]
	s_nop 0
	v_cndmask_b32_e64 v95, v249, v95, s[6:7]
.LBB0_724:
	v_add3_u32 v48, s43, v192, v193
	ds_read_b128 v[64:67], v48
	ds_read_b128 v[176:179], v48 offset:512
	ds_read_b128 v[168:171], v48 offset:2048
	ds_read_b128 v[152:155], v48 offset:2560
	ds_read_b128 v[172:175], v48 offset:4096
	ds_read_b128 v[148:151], v48 offset:4608
	ds_read_b128 v[164:167], v48 offset:6144
	ds_read_b128 v[144:147], v48 offset:6656
	ds_read_b128 v[160:163], v48 offset:8192
	ds_read_b128 v[140:143], v48 offset:8704
	ds_read_b128 v[156:159], v48 offset:10240
	ds_read_b128 v[136:139], v48 offset:10752
	s_nop 0
	v_max3_f32 v48, v96, v80, v97
	v_max3_f32 v49, v81, v98, v82
	v_max3_f32 v48, v48, v99, v83
	v_max3_f32 v49, v49, v100, v84
	v_max3_f32 v48, v48, v101, v85
	v_max3_f32 v49, v49, v102, v86
	v_max3_f32 v48, v48, v103, v87
	v_max3_f32 v49, v49, v104, v88
	v_max3_f32 v48, v48, v105, v89
	v_max3_f32 v49, v49, v106, v90
	v_max3_f32 v48, v48, v107, v91
	v_max3_f32 v49, v49, v108, v92
	v_max3_f32 v48, v48, v109, v93
	v_max3_f32 v49, v49, v110, v94
	v_max3_f32 v48, v48, v111, v95
	v_max_f32_e32 v48, v48, v49
	v_mov_b32_e32 v49, v48
	s_nop 1
	v_permlane32_swap_b32_e32 v48, v49
	v_max_f32_e32 v48, v48, v49
	v_cmp_lt_f32_e32 vcc, s97, v48
	v_cmp_lg_f32_e64 s[4:5], s96, v48
	s_nop 1
	s_and_b64 s[6:7], vcc, s[2:3]
	s_andn2_b64 vcc, s[4:5], s[2:3]
	s_or_b64 s[6:7], s[6:7], vcc
	s_and_b64 vcc, s[6:7], exec
	s_cbranch_vccz .LBB0_715
	v_cndmask_b32_e64 v32, 0, v48, s[6:7]
	v_exp_f32_e64 v34, -v32
	s_or_b64 s[4:5], s[2:3], s[4:5]
	v_add_f32_e32 v197, v197, v32
	v_pk_add_f32 v[96:97], v[96:97], v[32:33] op_sel_hi:[1,0] neg_lo:[0,1] neg_hi:[0,1]
	v_pk_add_f32 v[80:81], v[80:81], v[32:33] op_sel_hi:[1,0] neg_lo:[0,1] neg_hi:[0,1]
	v_pk_add_f32 v[98:99], v[98:99], v[32:33] op_sel_hi:[1,0] neg_lo:[0,1] neg_hi:[0,1]
	v_pk_add_f32 v[82:83], v[82:83], v[32:33] op_sel_hi:[1,0] neg_lo:[0,1] neg_hi:[0,1]
	v_pk_add_f32 v[100:101], v[100:101], v[32:33] op_sel_hi:[1,0] neg_lo:[0,1] neg_hi:[0,1]
	v_pk_add_f32 v[84:85], v[84:85], v[32:33] op_sel_hi:[1,0] neg_lo:[0,1] neg_hi:[0,1]
	v_pk_add_f32 v[102:103], v[102:103], v[32:33] op_sel_hi:[1,0] neg_lo:[0,1] neg_hi:[0,1]
	v_pk_add_f32 v[86:87], v[86:87], v[32:33] op_sel_hi:[1,0] neg_lo:[0,1] neg_hi:[0,1]
	v_pk_add_f32 v[104:105], v[104:105], v[32:33] op_sel_hi:[1,0] neg_lo:[0,1] neg_hi:[0,1]
	v_pk_add_f32 v[88:89], v[88:89], v[32:33] op_sel_hi:[1,0] neg_lo:[0,1] neg_hi:[0,1]
	v_pk_add_f32 v[106:107], v[106:107], v[32:33] op_sel_hi:[1,0] neg_lo:[0,1] neg_hi:[0,1]
	v_pk_add_f32 v[90:91], v[90:91], v[32:33] op_sel_hi:[1,0] neg_lo:[0,1] neg_hi:[0,1]
	v_pk_add_f32 v[108:109], v[108:109], v[32:33] op_sel_hi:[1,0] neg_lo:[0,1] neg_hi:[0,1]
	v_pk_add_f32 v[92:93], v[92:93], v[32:33] op_sel_hi:[1,0] neg_lo:[0,1] neg_hi:[0,1]
	v_pk_add_f32 v[110:111], v[110:111], v[32:33] op_sel_hi:[1,0] neg_lo:[0,1] neg_hi:[0,1]
	v_pk_add_f32 v[94:95], v[94:95], v[32:33] op_sel_hi:[1,0] neg_lo:[0,1] neg_hi:[0,1]
	v_xor_b32_e32 v32, 0x80000000, v197
	s_andn2_b64 s[2:3], s[2:3], exec
	s_and_b64 s[4:5], s[4:5], exec
	v_mul_f32_e32 v198, v198, v34
	v_pk_mul_f32 v[30:31], v[30:31], v[34:35] op_sel_hi:[1,0]
	v_pk_mul_f32 v[28:29], v[28:29], v[34:35] op_sel_hi:[1,0]
	v_pk_mul_f32 v[26:27], v[26:27], v[34:35] op_sel_hi:[1,0]
	v_pk_mul_f32 v[24:25], v[24:25], v[34:35] op_sel_hi:[1,0]
	v_pk_mul_f32 v[22:23], v[22:23], v[34:35] op_sel_hi:[1,0]
	v_pk_mul_f32 v[20:21], v[20:21], v[34:35] op_sel_hi:[1,0]
	v_pk_mul_f32 v[18:19], v[18:19], v[34:35] op_sel_hi:[1,0]
	v_pk_mul_f32 v[16:17], v[16:17], v[34:35] op_sel_hi:[1,0]
	v_pk_mul_f32 v[14:15], v[14:15], v[34:35] op_sel_hi:[1,0]
	v_pk_mul_f32 v[12:13], v[12:13], v[34:35] op_sel_hi:[1,0]
	v_pk_mul_f32 v[10:11], v[10:11], v[34:35] op_sel_hi:[1,0]
	v_pk_mul_f32 v[8:9], v[8:9], v[34:35] op_sel_hi:[1,0]
	v_pk_mul_f32 v[6:7], v[6:7], v[34:35] op_sel_hi:[1,0]
	v_pk_mul_f32 v[4:5], v[4:5], v[34:35] op_sel_hi:[1,0]
	v_pk_mul_f32 v[2:3], v[2:3], v[34:35] op_sel_hi:[1,0]
	v_pk_mul_f32 v[0:1], v[0:1], v[34:35] op_sel_hi:[1,0]
	v_mov_b32_e32 v33, v32
	v_mov_b32_e32 v34, v32
	v_mov_b32_e32 v35, v32
	v_mov_b32_e32 v36, v32
	v_mov_b32_e32 v37, v32
	v_mov_b32_e32 v38, v32
	v_mov_b32_e32 v39, v32
	v_mov_b32_e32 v40, v32
	v_mov_b32_e32 v41, v32
	v_mov_b32_e32 v42, v32
	v_mov_b32_e32 v43, v32
	v_mov_b32_e32 v44, v32
	v_mov_b32_e32 v45, v32
	v_mov_b32_e32 v46, v32
	v_mov_b32_e32 v47, v32
	s_or_b64 s[2:3], s[2:3], s[4:5]
	s_branch .LBB0_715

.LBB0_732:
	s_add_i32 s4, s21, -1
	s_min_u32 s4, s4, s40
	s_mul_hi_u32 s5, s4, 0x55555556
	s_mul_i32 s5, s5, 3
	s_sub_i32 s5, s4, s5
	s_mul_i32 s4, s4, 0x28000
	s_add_i32 s46, s21, -2
	s_mulk_i32 s5, 0x3000
	s_lshl_b32 s80, s4, 1
	s_min_u32 s4, s46, s40
	s_add_i32 s48, s5, 0
	s_mul_hi_u32 s5, s4, 0x55555556
	s_mul_i32 s5, s5, 3
	s_sub_i32 s5, s4, s5
	v_lshl_add_u64 v[80:81], v[128:129], 0, s[80:81]
	s_mulk_i32 s5, 0x3000
	v_lshl_add_u64 v[80:81], v[80:81], 0, s[76:77]
	s_add_i32 m0, s48, s92
	s_add_i32 s47, s5, 0
	s_mul_i32 s4, s4, 0x50000
	s_mov_b32 s5, s81
	global_load_lds_dwordx4 v[80:81], off
	v_lshl_add_u64 v[80:81], v[130:131], 0, s[4:5]
	s_add_i32 s4, s47, s95
	v_lshl_add_u64 v[80:81], v[80:81], 0, s[0:1]
	s_add_i32 m0, s4, 0x1000
	s_sub_i32 s4, s45, 64
	global_load_lds_dwordx4 v[80:81], off
	s_cmp_le_u32 s4, s39
	s_cbranch_scc1 .LBB0_734
	v_cmp_lt_i32_e64 s[4:5], -1, v136
	v_cmp_lt_i32_e64 s[6:7], 31, v136
	v_cmp_lt_i32_e32 vcc, 0, v136
	v_cndmask_b32_e64 v48, v249, v48, s[4:5]
	v_cmp_lt_i32_e64 s[4:5], 32, v136
	v_cndmask_b32_e64 v64, v249, v64, s[6:7]
	v_cmp_lt_i32_e64 s[6:7], 1, v136
	v_cndmask_b32_e32 v49, v249, v49, vcc
	v_cmp_lt_i32_e32 vcc, 33, v136
	v_cndmask_b32_e64 v65, v249, v65, s[4:5]
	v_cmp_lt_i32_e64 s[4:5], 2, v136
	v_cndmask_b32_e64 v50, v249, v50, s[6:7]
	v_cmp_lt_i32_e64 s[6:7], 34, v136
	v_cndmask_b32_e32 v66, v249, v66, vcc
	v_cmp_lt_i32_e32 vcc, 7, v136
	v_cndmask_b32_e64 v51, v249, v51, s[4:5]
	v_cmp_lt_i32_e64 s[4:5], 39, v136
	v_cndmask_b32_e64 v67, v249, v67, s[6:7]
	v_cmp_lt_i32_e64 s[6:7], 8, v136
	v_cndmask_b32_e32 v52, v249, v52, vcc
	v_cmp_lt_i32_e32 vcc, 40, v136
	v_cndmask_b32_e64 v68, v249, v68, s[4:5]
	v_cmp_lt_i32_e64 s[4:5], 9, v136
	v_cndmask_b32_e64 v53, v249, v53, s[6:7]
	v_cmp_lt_i32_e64 s[6:7], 41, v136
	v_cndmask_b32_e32 v69, v249, v69, vcc
	v_cmp_lt_i32_e32 vcc, 10, v136
	v_cndmask_b32_e64 v54, v249, v54, s[4:5]
	v_cmp_lt_i32_e64 s[4:5], 42, v136
	v_cndmask_b32_e64 v70, v249, v70, s[6:7]
	v_cmp_lt_i32_e64 s[6:7], 15, v136
	v_cndmask_b32_e32 v55, v249, v55, vcc
	v_cmp_lt_i32_e32 vcc, 47, v136
	v_cndmask_b32_e64 v71, v249, v71, s[4:5]
	v_cmp_lt_i32_e64 s[4:5], 16, v136
	v_cndmask_b32_e64 v56, v249, v56, s[6:7]
	v_cmp_lt_i32_e64 s[6:7], 48, v136
	v_cndmask_b32_e32 v72, v249, v72, vcc
	v_cmp_lt_i32_e32 vcc, 17, v136
	v_cndmask_b32_e64 v57, v249, v57, s[4:5]
	v_cmp_lt_i32_e64 s[4:5], 49, v136
	v_cndmask_b32_e64 v73, v249, v73, s[6:7]
	v_cmp_lt_i32_e64 s[6:7], 18, v136
	v_cndmask_b32_e32 v58, v249, v58, vcc
	v_cmp_lt_i32_e32 vcc, 50, v136
	v_cndmask_b32_e64 v74, v249, v74, s[4:5]
	v_cmp_lt_i32_e64 s[4:5], 23, v136
	v_cndmask_b32_e64 v59, v249, v59, s[6:7]
	v_cmp_lt_i32_e64 s[6:7], 55, v136
	v_cndmask_b32_e32 v75, v249, v75, vcc
	v_cmp_lt_i32_e32 vcc, 24, v136
	v_cndmask_b32_e64 v60, v249, v60, s[4:5]
	v_cmp_lt_i32_e64 s[4:5], 56, v136
	v_cndmask_b32_e64 v76, v249, v76, s[6:7]
	v_cmp_lt_i32_e64 s[6:7], 25, v136
	v_cndmask_b32_e32 v61, v249, v61, vcc
	v_cmp_lt_i32_e32 vcc, 57, v136
	v_cndmask_b32_e64 v77, v249, v77, s[4:5]
	v_cmp_lt_i32_e64 s[4:5], 26, v136
	v_cndmask_b32_e64 v62, v249, v62, s[6:7]
	v_cmp_lt_i32_e64 s[6:7], 58, v136
	v_cndmask_b32_e32 v78, v249, v78, vcc
	s_nop 0
	v_cndmask_b32_e64 v63, v249, v63, s[4:5]
	s_nop 0
	v_cndmask_b32_e64 v79, v249, v79, s[6:7]
.LBB0_734:
	s_add_i32 s4, s21, -3
	s_min_u32 s4, s4, s40
	s_mul_hi_u32 s5, s4, 0x55555556
	s_mul_i32 s5, s5, 3
	s_sub_i32 s4, s4, s5
	s_mulk_i32 s4, 0x3000
	v_add_u32_e32 v88, s4, v134
	ds_read_b128 v[84:87], v88
	ds_read_b128 v[124:127], v88 offset:512
	ds_read_b128 v[80:83], v88 offset:2048
	ds_read_b128 v[120:123], v88 offset:2560
	s_nop 0
	v_max3_f32 v88, v48, v64, v49
	v_max3_f32 v89, v65, v50, v66
	v_max3_f32 v88, v88, v51, v67
	v_max3_f32 v89, v89, v52, v68
	v_max3_f32 v88, v88, v53, v69
	v_max3_f32 v89, v89, v54, v70
	v_max3_f32 v88, v88, v55, v71
	v_max3_f32 v89, v89, v56, v72
	v_max3_f32 v88, v88, v57, v73
	v_max3_f32 v89, v89, v58, v74
	v_max3_f32 v88, v88, v59, v75
	v_max3_f32 v89, v89, v60, v76
	v_max3_f32 v88, v88, v61, v77
	v_max3_f32 v89, v89, v62, v78
	v_max3_f32 v88, v88, v63, v79
	v_max_f32_e32 v88, v88, v89
	v_mov_b32_e32 v89, v88
	s_nop 1
	v_permlane32_swap_b32_e32 v88, v89
	v_max_f32_e32 v88, v88, v89
	v_cmp_lt_f32_e32 vcc, s97, v88
	v_cmp_lg_f32_e64 s[4:5], s96, v88
	s_nop 1
	s_and_b64 s[6:7], vcc, s[2:3]
	s_andn2_b64 vcc, s[4:5], s[2:3]
	s_or_b64 s[6:7], s[6:7], vcc
	s_and_b64 vcc, s[6:7], exec
	s_cbranch_vccz .LBB0_736
	v_cndmask_b32_e64 v32, 0, v88, s[6:7]
	v_exp_f32_e64 v34, -v32
	s_or_b64 s[4:5], s[2:3], s[4:5]
	v_add_f32_e32 v137, v137, v32
	v_pk_add_f32 v[48:49], v[48:49], v[32:33] op_sel_hi:[1,0] neg_lo:[0,1] neg_hi:[0,1]
	v_pk_add_f32 v[64:65], v[64:65], v[32:33] op_sel_hi:[1,0] neg_lo:[0,1] neg_hi:[0,1]
	v_pk_add_f32 v[50:51], v[50:51], v[32:33] op_sel_hi:[1,0] neg_lo:[0,1] neg_hi:[0,1]
	v_pk_add_f32 v[66:67], v[66:67], v[32:33] op_sel_hi:[1,0] neg_lo:[0,1] neg_hi:[0,1]
	v_pk_add_f32 v[52:53], v[52:53], v[32:33] op_sel_hi:[1,0] neg_lo:[0,1] neg_hi:[0,1]
	v_pk_add_f32 v[68:69], v[68:69], v[32:33] op_sel_hi:[1,0] neg_lo:[0,1] neg_hi:[0,1]
	v_pk_add_f32 v[54:55], v[54:55], v[32:33] op_sel_hi:[1,0] neg_lo:[0,1] neg_hi:[0,1]
	v_pk_add_f32 v[70:71], v[70:71], v[32:33] op_sel_hi:[1,0] neg_lo:[0,1] neg_hi:[0,1]
	v_pk_add_f32 v[56:57], v[56:57], v[32:33] op_sel_hi:[1,0] neg_lo:[0,1] neg_hi:[0,1]
	v_pk_add_f32 v[72:73], v[72:73], v[32:33] op_sel_hi:[1,0] neg_lo:[0,1] neg_hi:[0,1]
	v_pk_add_f32 v[58:59], v[58:59], v[32:33] op_sel_hi:[1,0] neg_lo:[0,1] neg_hi:[0,1]
	v_pk_add_f32 v[74:75], v[74:75], v[32:33] op_sel_hi:[1,0] neg_lo:[0,1] neg_hi:[0,1]
	v_pk_add_f32 v[60:61], v[60:61], v[32:33] op_sel_hi:[1,0] neg_lo:[0,1] neg_hi:[0,1]
	v_pk_add_f32 v[76:77], v[76:77], v[32:33] op_sel_hi:[1,0] neg_lo:[0,1] neg_hi:[0,1]
	v_pk_add_f32 v[62:63], v[62:63], v[32:33] op_sel_hi:[1,0] neg_lo:[0,1] neg_hi:[0,1]
	v_pk_add_f32 v[78:79], v[78:79], v[32:33] op_sel_hi:[1,0] neg_lo:[0,1] neg_hi:[0,1]
	v_xor_b32_e32 v32, 0x80000000, v137
	s_andn2_b64 s[2:3], s[2:3], exec
	s_and_b64 s[4:5], s[4:5], exec
	v_mul_f32_e32 v138, v138, v34
	v_pk_mul_f32 v[30:31], v[30:31], v[34:35] op_sel_hi:[1,0]
	v_pk_mul_f32 v[28:29], v[28:29], v[34:35] op_sel_hi:[1,0]
	v_pk_mul_f32 v[26:27], v[26:27], v[34:35] op_sel_hi:[1,0]
	v_pk_mul_f32 v[24:25], v[24:25], v[34:35] op_sel_hi:[1,0]
	v_pk_mul_f32 v[22:23], v[22:23], v[34:35] op_sel_hi:[1,0]
	v_pk_mul_f32 v[20:21], v[20:21], v[34:35] op_sel_hi:[1,0]
	v_pk_mul_f32 v[18:19], v[18:19], v[34:35] op_sel_hi:[1,0]
	v_pk_mul_f32 v[16:17], v[16:17], v[34:35] op_sel_hi:[1,0]
	v_pk_mul_f32 v[14:15], v[14:15], v[34:35] op_sel_hi:[1,0]
	v_pk_mul_f32 v[12:13], v[12:13], v[34:35] op_sel_hi:[1,0]
	v_pk_mul_f32 v[10:11], v[10:11], v[34:35] op_sel_hi:[1,0]
	v_pk_mul_f32 v[8:9], v[8:9], v[34:35] op_sel_hi:[1,0]
	v_pk_mul_f32 v[6:7], v[6:7], v[34:35] op_sel_hi:[1,0]
	v_pk_mul_f32 v[4:5], v[4:5], v[34:35] op_sel_hi:[1,0]
	v_pk_mul_f32 v[2:3], v[2:3], v[34:35] op_sel_hi:[1,0]
	v_pk_mul_f32 v[0:1], v[0:1], v[34:35] op_sel_hi:[1,0]
	v_mov_b32_e32 v33, v32
	v_mov_b32_e32 v34, v32
	v_mov_b32_e32 v35, v32
	v_mov_b32_e32 v36, v32
	v_mov_b32_e32 v37, v32
	v_mov_b32_e32 v38, v32
	v_mov_b32_e32 v39, v32
	v_mov_b32_e32 v40, v32
	v_mov_b32_e32 v41, v32
	v_mov_b32_e32 v42, v32
	v_mov_b32_e32 v43, v32
	v_mov_b32_e32 v44, v32
	v_mov_b32_e32 v45, v32
	v_mov_b32_e32 v46, v32
	v_mov_b32_e32 v47, v32
	s_or_b64 s[2:3], s[2:3], s[4:5]
.LBB0_736:
	s_mul_hi_u32 s5, s44, 0xaaaaaaab
	s_lshr_b32 s5, s5, 1
	s_add_i32 s4, s21, -4
	s_mul_i32 s5, s5, 0xffff7000
	s_waitcnt lgkmcnt(0)
	v_mfma_f32_32x32x16_bf16 v[96:111], v[84:87], v[112:115], v[32:47]
	v_add_u32_e32 v139, s5, v135
	v_exp_f32_e32 v48, v48
	v_exp_f32_e32 v49, v49
	v_exp_f32_e32 v50, v50
	v_exp_f32_e32 v51, v51
	v_exp_f32_e32 v52, v52
	v_exp_f32_e32 v53, v53
	v_exp_f32_e32 v54, v54
	v_exp_f32_e32 v55, v55
	v_mfma_f32_32x32x16_bf16 v[96:111], v[80:83], v[116:119], v[96:111]
	v_exp_f32_e32 v56, v56
	v_exp_f32_e32 v57, v57
	v_exp_f32_e32 v58, v58
	v_exp_f32_e32 v59, v59
	v_exp_f32_e32 v60, v60
	v_exp_f32_e32 v61, v61
	v_exp_f32_e32 v62, v62
	v_exp_f32_e32 v63, v63
	v_mfma_f32_32x32x16_bf16 v[80:95], v[124:127], v[112:115], v[32:47]
	ds_read_b64_tr_b16 v[140:141], v139 offset:4096
	ds_read_b64_tr_b16 v[142:143], v139 offset:4608
	ds_read_b64_tr_b16 v[144:145], v139 offset:5120
	ds_read_b64_tr_b16 v[146:147], v139 offset:5632
	ds_read_b64_tr_b16 v[148:149], v139 offset:8192
	ds_read_b64_tr_b16 v[150:151], v139 offset:8704
	ds_read_b64_tr_b16 v[152:153], v139 offset:9216
	ds_read_b64_tr_b16 v[154:155], v139 offset:9728
	s_nop 1
	s_nop 0
	v_add_f32_e32 v124, v215, v48
	v_add_f32_e32 v125, v215, v49
	v_cvt_pk_bf16_f32 v126, v52, v53
	v_add_f32_e32 v124, v124, v50
	v_add_f32_e32 v125, v125, v51
	v_cvt_pk_bf16_f32 v127, v54, v55
	v_add_f32_e32 v124, v124, v52
	v_add_f32_e32 v125, v125, v53
	v_cvt_pk_bf16_f32 v156, v56, v57
	v_add_f32_e32 v124, v124, v54
	v_add_f32_e32 v125, v125, v55
	v_cvt_pk_bf16_f32 v157, v58, v59
	v_add_f32_e32 v124, v124, v56
	v_add_f32_e32 v125, v125, v57
	v_cvt_pk_bf16_f32 v158, v60, v61
	v_add_f32_e32 v124, v124, v58
	v_add_f32_e32 v125, v125, v59
	v_cvt_pk_bf16_f32 v159, v62, v63
	v_add_f32_e32 v124, v124, v60
	v_add_f32_e32 v125, v125, v61
	v_add_f32_e32 v160, v124, v62
	v_add_f32_e32 v161, v125, v63
	v_cvt_pk_bf16_f32 v124, v48, v49
	v_cvt_pk_bf16_f32 v125, v50, v51
	s_waitcnt lgkmcnt(0)
	s_nop 0
	v_mfma_f32_32x32x16_bf16 v[0:15], v[140:143], v[124:127], v[0:15]
	v_exp_f32_e32 v64, v64
	v_exp_f32_e32 v65, v65
	v_exp_f32_e32 v66, v66
	v_exp_f32_e32 v67, v67
	v_exp_f32_e32 v68, v68
	v_exp_f32_e32 v69, v69
	v_exp_f32_e32 v70, v70
	v_mfma_f32_32x32x16_bf16 v[16:31], v[148:151], v[124:127], v[16:31]
	v_exp_f32_e32 v71, v71
	v_exp_f32_e32 v72, v72
	v_exp_f32_e32 v73, v73
	v_exp_f32_e32 v74, v74
	v_exp_f32_e32 v75, v75
	v_exp_f32_e32 v76, v76
	v_exp_f32_e32 v77, v77
	v_mfma_f32_32x32x16_bf16 v[0:15], v[144:147], v[156:159], v[0:15]
	ds_read_b64_tr_b16 v[124:125], v139 offset:6144
	ds_read_b64_tr_b16 v[126:127], v139 offset:6656
	ds_read_b64_tr_b16 v[140:141], v139 offset:10240
	ds_read_b64_tr_b16 v[142:143], v139 offset:10752
	ds_read_b64_tr_b16 v[144:145], v139 offset:7168
	ds_read_b64_tr_b16 v[146:147], v139 offset:7680
	ds_read_b64_tr_b16 v[148:149], v139 offset:11264
	ds_read_b64_tr_b16 v[150:151], v139 offset:11776
	v_exp_f32_e32 v78, v78
	v_exp_f32_e32 v79, v79
	s_nop 1
	s_nop 0
	v_add_f32_e32 v139, v160, v64
	v_mfma_f32_32x32x16_bf16 v[16:31], v[152:155], v[156:159], v[16:31]
	v_add_f32_e32 v152, v161, v65
	v_add_f32_e32 v139, v139, v66
	v_cvt_pk_bf16_f32 v153, v66, v67
	v_add_f32_e32 v152, v152, v67
	v_add_f32_e32 v139, v139, v68
	v_cvt_pk_bf16_f32 v154, v68, v69
	v_add_f32_e32 v152, v152, v69
	v_add_f32_e32 v139, v139, v70
	v_cvt_pk_bf16_f32 v155, v70, v71
	v_add_f32_e32 v152, v152, v71
	v_add_f32_e32 v139, v139, v72
	v_cvt_pk_bf16_f32 v156, v72, v73
	v_add_f32_e32 v152, v152, v73
	v_add_f32_e32 v139, v139, v74
	v_cvt_pk_bf16_f32 v157, v74, v75
	v_add_f32_e32 v152, v152, v75
	v_add_f32_e32 v139, v139, v76
	v_cvt_pk_bf16_f32 v158, v76, v77
	v_add_f32_e32 v152, v152, v77
	v_add_f32_e32 v139, v139, v78
	v_cvt_pk_bf16_f32 v159, v78, v79
	v_add_f32_e32 v160, v152, v79
	v_cvt_pk_bf16_f32 v152, v64, v65
	s_nop 0
	s_nop 0
	v_add_f32_e32 v139, v139, v160
	s_waitcnt lgkmcnt(0)
	v_mfma_f32_32x32x16_bf16 v[0:15], v[124:127], v[152:155], v[0:15]
	s_waitcnt vmcnt(2) lgkmcnt(0)
	s_barrier
	v_add_f32_e32 v138, v138, v139
	s_cmp_ge_u32 s4, s40
	v_mfma_f32_32x32x16_bf16 v[16:31], v[140:143], v[152:155], v[16:31]
	v_mfma_f32_32x32x16_bf16 v[0:15], v[144:147], v[156:159], v[0:15]
	v_mfma_f32_32x32x16_bf16 v[16:31], v[148:151], v[156:159], v[16:31]
	v_mfma_f32_32x32x16_bf16 v[80:95], v[120:123], v[116:119], v[80:95]
	s_cbranch_scc1 .LBB0_731
	s_min_u32 s4, s21, s40
	s_mul_hi_u32 s5, s4, 0x55555556
	s_mul_i32 s5, s5, 3
	s_sub_i32 s5, s4, s5
	s_mul_i32 s6, s5, 0x3000
	s_mul_i32 s4, s4, 0x50000
	s_mov_b32 s5, s81
	v_lshl_add_u64 v[48:49], v[128:129], 0, s[4:5]
	v_lshl_add_u64 v[48:49], v[48:49], 0, s[76:77]
	s_add_i32 m0, s93, s6
	s_add_i32 s4, s48, s95
	global_load_lds_dwordx4 v[48:49], off
	v_lshl_add_u64 v[48:49], v[130:131], 0, s[80:81]
	v_lshl_add_u64 v[48:49], v[48:49], 0, s[0:1]
	s_add_i32 m0, s4, 0x1000
	s_cmp_le_u32 s45, s39
	global_load_lds_dwordx4 v[48:49], off
	s_cbranch_scc1 .LBB0_739
	v_subrev_u32_e32 v48, 64, v136
	v_cmp_lt_i32_e64 s[4:5], -1, v48
	v_cmp_lt_i32_e64 s[6:7], 31, v48
	v_cmp_lt_i32_e32 vcc, 0, v48
	v_cndmask_b32_e64 v96, v249, v96, s[4:5]
	v_cmp_lt_i32_e64 s[4:5], 32, v48
	v_cndmask_b32_e64 v80, v249, v80, s[6:7]
	v_cmp_lt_i32_e64 s[6:7], 1, v48
	v_cndmask_b32_e32 v97, v249, v97, vcc
	v_cmp_lt_i32_e32 vcc, 33, v48
	v_cndmask_b32_e64 v81, v249, v81, s[4:5]
	v_cmp_lt_i32_e64 s[4:5], 2, v48
	v_cndmask_b32_e64 v98, v249, v98, s[6:7]
	v_cmp_lt_i32_e64 s[6:7], 34, v48
	v_cndmask_b32_e32 v82, v249, v82, vcc
	v_cmp_lt_i32_e32 vcc, 7, v48
	v_cndmask_b32_e64 v99, v249, v99, s[4:5]
	v_cmp_lt_i32_e64 s[4:5], 39, v48
	v_cndmask_b32_e64 v83, v249, v83, s[6:7]
	v_cmp_lt_i32_e64 s[6:7], 8, v48
	v_cndmask_b32_e32 v100, v249, v100, vcc
	v_cmp_lt_i32_e32 vcc, 40, v48
	v_cndmask_b32_e64 v84, v249, v84, s[4:5]
	v_cmp_lt_i32_e64 s[4:5], 9, v48
	v_cndmask_b32_e64 v101, v249, v101, s[6:7]
	v_cmp_lt_i32_e64 s[6:7], 41, v48
	v_cndmask_b32_e32 v85, v249, v85, vcc
	v_cmp_lt_i32_e32 vcc, 10, v48
	v_cndmask_b32_e64 v102, v249, v102, s[4:5]
	v_cmp_lt_i32_e64 s[4:5], 42, v48
	v_cndmask_b32_e64 v86, v249, v86, s[6:7]
	v_cmp_lt_i32_e64 s[6:7], 15, v48
	v_cndmask_b32_e32 v103, v249, v103, vcc
	v_cmp_lt_i32_e32 vcc, 47, v48
	v_cndmask_b32_e64 v87, v249, v87, s[4:5]
	v_cmp_lt_i32_e64 s[4:5], 16, v48
	v_cndmask_b32_e64 v104, v249, v104, s[6:7]
	v_cmp_lt_i32_e64 s[6:7], 48, v48
	v_cndmask_b32_e32 v88, v249, v88, vcc
	v_cmp_lt_i32_e32 vcc, 17, v48
	v_cndmask_b32_e64 v105, v249, v105, s[4:5]
	v_cmp_lt_i32_e64 s[4:5], 49, v48
	v_cndmask_b32_e64 v89, v249, v89, s[6:7]
	v_cmp_lt_i32_e64 s[6:7], 18, v48
	v_cndmask_b32_e32 v106, v249, v106, vcc
	v_cmp_lt_i32_e32 vcc, 50, v48
	v_cndmask_b32_e64 v90, v249, v90, s[4:5]
	v_cmp_lt_i32_e64 s[4:5], 23, v48
	v_cndmask_b32_e64 v107, v249, v107, s[6:7]
	v_cmp_lt_i32_e64 s[6:7], 55, v48
	v_cndmask_b32_e32 v91, v249, v91, vcc
	v_cmp_lt_i32_e32 vcc, 24, v48
	v_cndmask_b32_e64 v108, v249, v108, s[4:5]
	v_cmp_lt_i32_e64 s[4:5], 56, v48
	v_cndmask_b32_e64 v92, v249, v92, s[6:7]
	v_cmp_lt_i32_e64 s[6:7], 25, v48
	v_cndmask_b32_e32 v109, v249, v109, vcc
	v_cmp_lt_i32_e32 vcc, 57, v48
	v_cndmask_b32_e64 v93, v249, v93, s[4:5]
	v_cmp_lt_i32_e64 s[4:5], 26, v48
	v_cndmask_b32_e64 v110, v249, v110, s[6:7]
	v_cmp_lt_i32_e64 s[6:7], 58, v48
	v_cndmask_b32_e32 v94, v249, v94, vcc
	s_nop 0
	v_cndmask_b32_e64 v111, v249, v111, s[4:5]
	s_nop 0
	v_cndmask_b32_e64 v95, v249, v95, s[6:7]
.LBB0_739:
	v_add3_u32 v48, s47, v132, v133
	ds_read_b128 v[68:71], v48
	ds_read_b128 v[124:127], v48 offset:512
	ds_read_b128 v[64:67], v48 offset:2048
	ds_read_b128 v[120:123], v48 offset:2560
	s_nop 0
	v_max3_f32 v48, v96, v80, v97
	v_max3_f32 v49, v81, v98, v82
	v_max3_f32 v48, v48, v99, v83
	v_max3_f32 v49, v49, v100, v84
	v_max3_f32 v48, v48, v101, v85
	v_max3_f32 v49, v49, v102, v86
	v_max3_f32 v48, v48, v103, v87
	v_max3_f32 v49, v49, v104, v88
	v_max3_f32 v48, v48, v105, v89
	v_max3_f32 v49, v49, v106, v90
	v_max3_f32 v48, v48, v107, v91
	v_max3_f32 v49, v49, v108, v92
	v_max3_f32 v48, v48, v109, v93
	v_max3_f32 v49, v49, v110, v94
	v_max3_f32 v48, v48, v111, v95
	v_max_f32_e32 v48, v48, v49
	v_mov_b32_e32 v49, v48
	s_nop 1
	v_permlane32_swap_b32_e32 v48, v49
	v_max_f32_e32 v48, v48, v49
	v_cmp_lt_f32_e32 vcc, s97, v48
	v_cmp_lg_f32_e64 s[4:5], s96, v48
	s_nop 1
	s_and_b64 s[6:7], vcc, s[2:3]
	s_andn2_b64 vcc, s[4:5], s[2:3]
	s_or_b64 s[6:7], s[6:7], vcc
	s_and_b64 vcc, s[6:7], exec
	s_cbranch_vccz .LBB0_730
	v_cndmask_b32_e64 v32, 0, v48, s[6:7]
	v_exp_f32_e64 v34, -v32
	s_or_b64 s[4:5], s[2:3], s[4:5]
	v_add_f32_e32 v137, v137, v32
	v_pk_add_f32 v[96:97], v[96:97], v[32:33] op_sel_hi:[1,0] neg_lo:[0,1] neg_hi:[0,1]
	v_pk_add_f32 v[80:81], v[80:81], v[32:33] op_sel_hi:[1,0] neg_lo:[0,1] neg_hi:[0,1]
	v_pk_add_f32 v[98:99], v[98:99], v[32:33] op_sel_hi:[1,0] neg_lo:[0,1] neg_hi:[0,1]
	v_pk_add_f32 v[82:83], v[82:83], v[32:33] op_sel_hi:[1,0] neg_lo:[0,1] neg_hi:[0,1]
	v_pk_add_f32 v[100:101], v[100:101], v[32:33] op_sel_hi:[1,0] neg_lo:[0,1] neg_hi:[0,1]
	v_pk_add_f32 v[84:85], v[84:85], v[32:33] op_sel_hi:[1,0] neg_lo:[0,1] neg_hi:[0,1]
	v_pk_add_f32 v[102:103], v[102:103], v[32:33] op_sel_hi:[1,0] neg_lo:[0,1] neg_hi:[0,1]
	v_pk_add_f32 v[86:87], v[86:87], v[32:33] op_sel_hi:[1,0] neg_lo:[0,1] neg_hi:[0,1]
	v_pk_add_f32 v[104:105], v[104:105], v[32:33] op_sel_hi:[1,0] neg_lo:[0,1] neg_hi:[0,1]
	v_pk_add_f32 v[88:89], v[88:89], v[32:33] op_sel_hi:[1,0] neg_lo:[0,1] neg_hi:[0,1]
	v_pk_add_f32 v[106:107], v[106:107], v[32:33] op_sel_hi:[1,0] neg_lo:[0,1] neg_hi:[0,1]
	v_pk_add_f32 v[90:91], v[90:91], v[32:33] op_sel_hi:[1,0] neg_lo:[0,1] neg_hi:[0,1]
	v_pk_add_f32 v[108:109], v[108:109], v[32:33] op_sel_hi:[1,0] neg_lo:[0,1] neg_hi:[0,1]
	v_pk_add_f32 v[92:93], v[92:93], v[32:33] op_sel_hi:[1,0] neg_lo:[0,1] neg_hi:[0,1]
	v_pk_add_f32 v[110:111], v[110:111], v[32:33] op_sel_hi:[1,0] neg_lo:[0,1] neg_hi:[0,1]
	v_pk_add_f32 v[94:95], v[94:95], v[32:33] op_sel_hi:[1,0] neg_lo:[0,1] neg_hi:[0,1]
	v_xor_b32_e32 v32, 0x80000000, v137
	s_andn2_b64 s[2:3], s[2:3], exec
	s_and_b64 s[4:5], s[4:5], exec
	v_mul_f32_e32 v138, v138, v34
	v_pk_mul_f32 v[30:31], v[30:31], v[34:35] op_sel_hi:[1,0]
	v_pk_mul_f32 v[28:29], v[28:29], v[34:35] op_sel_hi:[1,0]
	v_pk_mul_f32 v[26:27], v[26:27], v[34:35] op_sel_hi:[1,0]
	v_pk_mul_f32 v[24:25], v[24:25], v[34:35] op_sel_hi:[1,0]
	v_pk_mul_f32 v[22:23], v[22:23], v[34:35] op_sel_hi:[1,0]
	v_pk_mul_f32 v[20:21], v[20:21], v[34:35] op_sel_hi:[1,0]
	v_pk_mul_f32 v[18:19], v[18:19], v[34:35] op_sel_hi:[1,0]
	v_pk_mul_f32 v[16:17], v[16:17], v[34:35] op_sel_hi:[1,0]
	v_pk_mul_f32 v[14:15], v[14:15], v[34:35] op_sel_hi:[1,0]
	v_pk_mul_f32 v[12:13], v[12:13], v[34:35] op_sel_hi:[1,0]
	v_pk_mul_f32 v[10:11], v[10:11], v[34:35] op_sel_hi:[1,0]
	v_pk_mul_f32 v[8:9], v[8:9], v[34:35] op_sel_hi:[1,0]
	v_pk_mul_f32 v[6:7], v[6:7], v[34:35] op_sel_hi:[1,0]
	v_pk_mul_f32 v[4:5], v[4:5], v[34:35] op_sel_hi:[1,0]
	v_pk_mul_f32 v[2:3], v[2:3], v[34:35] op_sel_hi:[1,0]
	v_pk_mul_f32 v[0:1], v[0:1], v[34:35] op_sel_hi:[1,0]
	v_mov_b32_e32 v33, v32
	v_mov_b32_e32 v34, v32
	v_mov_b32_e32 v35, v32
	v_mov_b32_e32 v36, v32
	v_mov_b32_e32 v37, v32
	v_mov_b32_e32 v38, v32
	v_mov_b32_e32 v39, v32
	v_mov_b32_e32 v40, v32
	v_mov_b32_e32 v41, v32
	v_mov_b32_e32 v42, v32
	v_mov_b32_e32 v43, v32
	v_mov_b32_e32 v44, v32
	v_mov_b32_e32 v45, v32
	v_mov_b32_e32 v46, v32
	v_mov_b32_e32 v47, v32
	s_or_b64 s[2:3], s[2:3], s[4:5]
	s_branch .LBB0_730

.LBB0_744:
	s_add_i32 s4, s17, -1
	s_min_u32 s4, s4, s40
	s_mul_hi_u32 s5, s4, 0x55555556
	s_mul_i32 s5, s5, 3
	s_sub_i32 s5, s4, s5
	s_mul_i32 s4, s4, 0x28000
	s_add_i32 s20, s17, -2
	s_mulk_i32 s5, 0x3000
	s_lshl_b32 s80, s4, 1
	s_min_u32 s4, s20, s40
	s_add_i32 s41, s5, 0
	s_mul_hi_u32 s5, s4, 0x55555556
	s_mul_i32 s5, s5, 3
	s_sub_i32 s5, s4, s5
	v_lshl_add_u64 v[80:81], v[128:129], 0, s[80:81]
	s_mulk_i32 s5, 0x3000
	v_lshl_add_u64 v[80:81], v[80:81], 0, s[90:91]
	s_add_i32 m0, s41, s92
	s_add_i32 s21, s5, 0
	s_mul_i32 s4, s4, 0x50000
	s_mov_b32 s5, s81
	global_load_lds_dwordx4 v[80:81], off
	v_lshl_add_u64 v[80:81], v[130:131], 0, s[4:5]
	s_add_i32 s4, s21, s95
	v_lshl_add_u64 v[80:81], v[80:81], 0, s[0:1]
	s_add_i32 m0, s4, 0x1000
	s_sub_i32 s4, s19, 64
	global_load_lds_dwordx4 v[80:81], off
	s_cmp_le_u32 s4, s39
	s_cbranch_scc1 .LBB0_746
	v_cmp_lt_i32_e64 s[4:5], -1, v137
	v_cmp_lt_i32_e64 s[6:7], 31, v137
	v_cmp_lt_i32_e32 vcc, 0, v137
	v_cndmask_b32_e64 v48, v249, v48, s[4:5]
	v_cmp_lt_i32_e64 s[4:5], 32, v137
	v_cndmask_b32_e64 v64, v249, v64, s[6:7]
	v_cmp_lt_i32_e64 s[6:7], 1, v137
	v_cndmask_b32_e32 v49, v249, v49, vcc
	v_cmp_lt_i32_e32 vcc, 33, v137
	v_cndmask_b32_e64 v65, v249, v65, s[4:5]
	v_cmp_lt_i32_e64 s[4:5], 2, v137
	v_cndmask_b32_e64 v50, v249, v50, s[6:7]
	v_cmp_lt_i32_e64 s[6:7], 34, v137
	v_cndmask_b32_e32 v66, v249, v66, vcc
	v_cmp_lt_i32_e32 vcc, 7, v137
	v_cndmask_b32_e64 v51, v249, v51, s[4:5]
	v_cmp_lt_i32_e64 s[4:5], 39, v137
	v_cndmask_b32_e64 v67, v249, v67, s[6:7]
	v_cmp_lt_i32_e64 s[6:7], 8, v137
	v_cndmask_b32_e32 v52, v249, v52, vcc
	v_cmp_lt_i32_e32 vcc, 40, v137
	v_cndmask_b32_e64 v68, v249, v68, s[4:5]
	v_cmp_lt_i32_e64 s[4:5], 9, v137
	v_cndmask_b32_e64 v53, v249, v53, s[6:7]
	v_cmp_lt_i32_e64 s[6:7], 41, v137
	v_cndmask_b32_e32 v69, v249, v69, vcc
	v_cmp_lt_i32_e32 vcc, 10, v137
	v_cndmask_b32_e64 v54, v249, v54, s[4:5]
	v_cmp_lt_i32_e64 s[4:5], 42, v137
	v_cndmask_b32_e64 v70, v249, v70, s[6:7]
	v_cmp_lt_i32_e64 s[6:7], 15, v137
	v_cndmask_b32_e32 v55, v249, v55, vcc
	v_cmp_lt_i32_e32 vcc, 47, v137
	v_cndmask_b32_e64 v71, v249, v71, s[4:5]
	v_cmp_lt_i32_e64 s[4:5], 16, v137
	v_cndmask_b32_e64 v56, v249, v56, s[6:7]
	v_cmp_lt_i32_e64 s[6:7], 48, v137
	v_cndmask_b32_e32 v72, v249, v72, vcc
	v_cmp_lt_i32_e32 vcc, 17, v137
	v_cndmask_b32_e64 v57, v249, v57, s[4:5]
	v_cmp_lt_i32_e64 s[4:5], 49, v137
	v_cndmask_b32_e64 v73, v249, v73, s[6:7]
	v_cmp_lt_i32_e64 s[6:7], 18, v137
	v_cndmask_b32_e32 v58, v249, v58, vcc
	v_cmp_lt_i32_e32 vcc, 50, v137
	v_cndmask_b32_e64 v74, v249, v74, s[4:5]
	v_cmp_lt_i32_e64 s[4:5], 23, v137
	v_cndmask_b32_e64 v59, v249, v59, s[6:7]
	v_cmp_lt_i32_e64 s[6:7], 55, v137
	v_cndmask_b32_e32 v75, v249, v75, vcc
	v_cmp_lt_i32_e32 vcc, 24, v137
	v_cndmask_b32_e64 v60, v249, v60, s[4:5]
	v_cmp_lt_i32_e64 s[4:5], 56, v137
	v_cndmask_b32_e64 v76, v249, v76, s[6:7]
	v_cmp_lt_i32_e64 s[6:7], 25, v137
	v_cndmask_b32_e32 v61, v249, v61, vcc
	v_cmp_lt_i32_e32 vcc, 57, v137
	v_cndmask_b32_e64 v77, v249, v77, s[4:5]
	v_cmp_lt_i32_e64 s[4:5], 26, v137
	v_cndmask_b32_e64 v62, v249, v62, s[6:7]
	v_cmp_lt_i32_e64 s[6:7], 58, v137
	v_cndmask_b32_e32 v78, v249, v78, vcc
	s_nop 0
	v_cndmask_b32_e64 v63, v249, v63, s[4:5]
	s_nop 0
	v_cndmask_b32_e64 v79, v249, v79, s[6:7]
.LBB0_746:
	s_add_i32 s4, s17, -3
	s_min_u32 s4, s4, s40
	s_mul_hi_u32 s5, s4, 0x55555556
	s_mul_i32 s5, s5, 3
	s_sub_i32 s4, s4, s5
	s_mulk_i32 s4, 0x3000
	v_add_u32_e32 v88, s4, v135
	ds_read_b128 v[84:87], v88
	ds_read_b128 v[124:127], v88 offset:512
	ds_read_b128 v[80:83], v88 offset:2048
	ds_read_b128 v[120:123], v88 offset:2560
	s_nop 0
	v_max3_f32 v88, v48, v64, v49
	v_max3_f32 v89, v65, v50, v66
	v_max3_f32 v88, v88, v51, v67
	v_max3_f32 v89, v89, v52, v68
	v_max3_f32 v88, v88, v53, v69
	v_max3_f32 v89, v89, v54, v70
	v_max3_f32 v88, v88, v55, v71
	v_max3_f32 v89, v89, v56, v72
	v_max3_f32 v88, v88, v57, v73
	v_max3_f32 v89, v89, v58, v74
	v_max3_f32 v88, v88, v59, v75
	v_max3_f32 v89, v89, v60, v76
	v_max3_f32 v88, v88, v61, v77
	v_max3_f32 v89, v89, v62, v78
	v_max3_f32 v88, v88, v63, v79
	v_max_f32_e32 v88, v88, v89
	v_mov_b32_e32 v89, v88
	s_nop 1
	v_permlane32_swap_b32_e32 v88, v89
	v_max_f32_e32 v88, v88, v89
	v_cmp_lt_f32_e32 vcc, s97, v88
	v_cmp_lg_f32_e64 s[4:5], s96, v88
	s_nop 1
	s_and_b64 s[6:7], vcc, s[2:3]
	s_andn2_b64 vcc, s[4:5], s[2:3]
	s_or_b64 s[6:7], s[6:7], vcc
	s_and_b64 vcc, s[6:7], exec
	s_cbranch_vccz .LBB0_748
	v_cndmask_b32_e64 v32, 0, v88, s[6:7]
	v_exp_f32_e64 v34, -v32
	s_or_b64 s[4:5], s[2:3], s[4:5]
	v_add_f32_e32 v138, v138, v32
	v_pk_add_f32 v[48:49], v[48:49], v[32:33] op_sel_hi:[1,0] neg_lo:[0,1] neg_hi:[0,1]
	v_pk_add_f32 v[64:65], v[64:65], v[32:33] op_sel_hi:[1,0] neg_lo:[0,1] neg_hi:[0,1]
	v_pk_add_f32 v[50:51], v[50:51], v[32:33] op_sel_hi:[1,0] neg_lo:[0,1] neg_hi:[0,1]
	v_pk_add_f32 v[66:67], v[66:67], v[32:33] op_sel_hi:[1,0] neg_lo:[0,1] neg_hi:[0,1]
	v_pk_add_f32 v[52:53], v[52:53], v[32:33] op_sel_hi:[1,0] neg_lo:[0,1] neg_hi:[0,1]
	v_pk_add_f32 v[68:69], v[68:69], v[32:33] op_sel_hi:[1,0] neg_lo:[0,1] neg_hi:[0,1]
	v_pk_add_f32 v[54:55], v[54:55], v[32:33] op_sel_hi:[1,0] neg_lo:[0,1] neg_hi:[0,1]
	v_pk_add_f32 v[70:71], v[70:71], v[32:33] op_sel_hi:[1,0] neg_lo:[0,1] neg_hi:[0,1]
	v_pk_add_f32 v[56:57], v[56:57], v[32:33] op_sel_hi:[1,0] neg_lo:[0,1] neg_hi:[0,1]
	v_pk_add_f32 v[72:73], v[72:73], v[32:33] op_sel_hi:[1,0] neg_lo:[0,1] neg_hi:[0,1]
	v_pk_add_f32 v[58:59], v[58:59], v[32:33] op_sel_hi:[1,0] neg_lo:[0,1] neg_hi:[0,1]
	v_pk_add_f32 v[74:75], v[74:75], v[32:33] op_sel_hi:[1,0] neg_lo:[0,1] neg_hi:[0,1]
	v_pk_add_f32 v[60:61], v[60:61], v[32:33] op_sel_hi:[1,0] neg_lo:[0,1] neg_hi:[0,1]
	v_pk_add_f32 v[76:77], v[76:77], v[32:33] op_sel_hi:[1,0] neg_lo:[0,1] neg_hi:[0,1]
	v_pk_add_f32 v[62:63], v[62:63], v[32:33] op_sel_hi:[1,0] neg_lo:[0,1] neg_hi:[0,1]
	v_pk_add_f32 v[78:79], v[78:79], v[32:33] op_sel_hi:[1,0] neg_lo:[0,1] neg_hi:[0,1]
	v_xor_b32_e32 v32, 0x80000000, v138
	s_andn2_b64 s[2:3], s[2:3], exec
	s_and_b64 s[4:5], s[4:5], exec
	v_mul_f32_e32 v139, v139, v34
	v_pk_mul_f32 v[30:31], v[30:31], v[34:35] op_sel_hi:[1,0]
	v_pk_mul_f32 v[28:29], v[28:29], v[34:35] op_sel_hi:[1,0]
	v_pk_mul_f32 v[26:27], v[26:27], v[34:35] op_sel_hi:[1,0]
	v_pk_mul_f32 v[24:25], v[24:25], v[34:35] op_sel_hi:[1,0]
	v_pk_mul_f32 v[22:23], v[22:23], v[34:35] op_sel_hi:[1,0]
	v_pk_mul_f32 v[20:21], v[20:21], v[34:35] op_sel_hi:[1,0]
	v_pk_mul_f32 v[18:19], v[18:19], v[34:35] op_sel_hi:[1,0]
	v_pk_mul_f32 v[16:17], v[16:17], v[34:35] op_sel_hi:[1,0]
	v_pk_mul_f32 v[14:15], v[14:15], v[34:35] op_sel_hi:[1,0]
	v_pk_mul_f32 v[12:13], v[12:13], v[34:35] op_sel_hi:[1,0]
	v_pk_mul_f32 v[10:11], v[10:11], v[34:35] op_sel_hi:[1,0]
	v_pk_mul_f32 v[8:9], v[8:9], v[34:35] op_sel_hi:[1,0]
	v_pk_mul_f32 v[6:7], v[6:7], v[34:35] op_sel_hi:[1,0]
	v_pk_mul_f32 v[4:5], v[4:5], v[34:35] op_sel_hi:[1,0]
	v_pk_mul_f32 v[2:3], v[2:3], v[34:35] op_sel_hi:[1,0]
	v_pk_mul_f32 v[0:1], v[0:1], v[34:35] op_sel_hi:[1,0]
	v_mov_b32_e32 v33, v32
	v_mov_b32_e32 v34, v32
	v_mov_b32_e32 v35, v32
	v_mov_b32_e32 v36, v32
	v_mov_b32_e32 v37, v32
	v_mov_b32_e32 v38, v32
	v_mov_b32_e32 v39, v32
	v_mov_b32_e32 v40, v32
	v_mov_b32_e32 v41, v32
	v_mov_b32_e32 v42, v32
	v_mov_b32_e32 v43, v32
	v_mov_b32_e32 v44, v32
	v_mov_b32_e32 v45, v32
	v_mov_b32_e32 v46, v32
	v_mov_b32_e32 v47, v32
	s_or_b64 s[2:3], s[2:3], s[4:5]
.LBB0_748:
	s_mul_hi_u32 s5, s16, 0xaaaaaaab
	s_lshr_b32 s5, s5, 1
	s_add_i32 s4, s17, -4
	s_mul_i32 s5, s5, 0xffff7000
	s_waitcnt lgkmcnt(0)
	v_mfma_f32_32x32x16_bf16 v[96:111], v[84:87], v[112:115], v[32:47]
	v_add_u32_e32 v160, s5, v136
	v_exp_f32_e32 v48, v48
	v_exp_f32_e32 v49, v49
	v_exp_f32_e32 v50, v50
	v_exp_f32_e32 v51, v51
	v_exp_f32_e32 v52, v52
	v_exp_f32_e32 v53, v53
	v_exp_f32_e32 v54, v54
	v_exp_f32_e32 v55, v55
	v_mfma_f32_32x32x16_bf16 v[96:111], v[80:83], v[116:119], v[96:111]
	v_exp_f32_e32 v56, v56
	v_exp_f32_e32 v57, v57
	v_exp_f32_e32 v58, v58
	v_exp_f32_e32 v59, v59
	v_exp_f32_e32 v60, v60
	v_exp_f32_e32 v61, v61
	v_exp_f32_e32 v62, v62
	v_exp_f32_e32 v63, v63
	v_mfma_f32_32x32x16_bf16 v[80:95], v[124:127], v[112:115], v[32:47]
	ds_read_b64_tr_b16 v[140:141], v160 offset:4096
	ds_read_b64_tr_b16 v[142:143], v160 offset:4608
	ds_read_b64_tr_b16 v[144:145], v160 offset:5120
	ds_read_b64_tr_b16 v[146:147], v160 offset:5632
	ds_read_b64_tr_b16 v[148:149], v160 offset:8192
	ds_read_b64_tr_b16 v[150:151], v160 offset:8704
	ds_read_b64_tr_b16 v[152:153], v160 offset:9216
	ds_read_b64_tr_b16 v[154:155], v160 offset:9728
	s_nop 1
	s_nop 0
	v_add_f32_e32 v124, v215, v48
	v_add_f32_e32 v125, v215, v49
	v_cvt_pk_bf16_f32 v126, v52, v53
	v_add_f32_e32 v124, v124, v50
	v_add_f32_e32 v125, v125, v51
	v_cvt_pk_bf16_f32 v127, v54, v55
	v_add_f32_e32 v124, v124, v52
	v_add_f32_e32 v125, v125, v53
	v_cvt_pk_bf16_f32 v156, v56, v57
	v_add_f32_e32 v124, v124, v54
	v_add_f32_e32 v125, v125, v55
	v_cvt_pk_bf16_f32 v157, v58, v59
	v_add_f32_e32 v124, v124, v56
	v_add_f32_e32 v125, v125, v57
	v_cvt_pk_bf16_f32 v158, v60, v61
	v_add_f32_e32 v124, v124, v58
	v_add_f32_e32 v125, v125, v59
	v_cvt_pk_bf16_f32 v159, v62, v63
	v_add_f32_e32 v124, v124, v60
	v_add_f32_e32 v125, v125, v61
	v_add_f32_e32 v161, v124, v62
	v_add_f32_e32 v162, v125, v63
	v_cvt_pk_bf16_f32 v124, v48, v49
	v_cvt_pk_bf16_f32 v125, v50, v51
	s_waitcnt lgkmcnt(0)
	s_nop 0
	v_mfma_f32_32x32x16_bf16 v[0:15], v[140:143], v[124:127], v[0:15]
	v_exp_f32_e32 v64, v64
	v_exp_f32_e32 v65, v65
	v_exp_f32_e32 v66, v66
	v_exp_f32_e32 v67, v67
	v_exp_f32_e32 v68, v68
	v_exp_f32_e32 v69, v69
	v_exp_f32_e32 v70, v70
	v_mfma_f32_32x32x16_bf16 v[16:31], v[148:151], v[124:127], v[16:31]
	v_exp_f32_e32 v71, v71
	v_exp_f32_e32 v72, v72
	v_exp_f32_e32 v73, v73
	v_exp_f32_e32 v74, v74
	v_exp_f32_e32 v75, v75
	v_exp_f32_e32 v76, v76
	v_exp_f32_e32 v77, v77
	v_mfma_f32_32x32x16_bf16 v[0:15], v[144:147], v[156:159], v[0:15]
	ds_read_b64_tr_b16 v[124:125], v160 offset:6144
	ds_read_b64_tr_b16 v[126:127], v160 offset:6656
	ds_read_b64_tr_b16 v[140:141], v160 offset:10240
	ds_read_b64_tr_b16 v[142:143], v160 offset:10752
	ds_read_b64_tr_b16 v[144:145], v160 offset:7168
	ds_read_b64_tr_b16 v[146:147], v160 offset:7680
	ds_read_b64_tr_b16 v[148:149], v160 offset:11264
	ds_read_b64_tr_b16 v[150:151], v160 offset:11776
	v_exp_f32_e32 v78, v78
	v_exp_f32_e32 v79, v79
	s_nop 1
	v_mfma_f32_32x32x16_bf16 v[16:31], v[152:155], v[156:159], v[16:31]
	v_add_f32_e32 v152, v161, v64
	v_add_f32_e32 v153, v162, v65
	v_cvt_pk_bf16_f32 v154, v68, v69
	v_add_f32_e32 v152, v152, v66
	v_add_f32_e32 v153, v153, v67
	v_cvt_pk_bf16_f32 v155, v70, v71
	v_add_f32_e32 v152, v152, v68
	v_add_f32_e32 v153, v153, v69
	v_cvt_pk_bf16_f32 v156, v72, v73
	v_add_f32_e32 v152, v152, v70
	v_add_f32_e32 v153, v153, v71
	v_cvt_pk_bf16_f32 v157, v74, v75
	v_add_f32_e32 v152, v152, v72
	v_add_f32_e32 v153, v153, v73
	v_cvt_pk_bf16_f32 v158, v76, v77
	v_add_f32_e32 v152, v152, v74
	v_add_f32_e32 v153, v153, v75
	v_cvt_pk_bf16_f32 v159, v78, v79
	v_add_f32_e32 v152, v152, v76
	v_add_f32_e32 v153, v153, v77
	v_add_f32_e32 v160, v152, v78
	v_add_f32_e32 v161, v153, v79
	v_cvt_pk_bf16_f32 v152, v64, v65
	s_nop 0
	v_cvt_pk_bf16_f32 v153, v66, v67
	v_add_f32_e32 v160, v160, v161
	s_waitcnt lgkmcnt(0)
	v_mfma_f32_32x32x16_bf16 v[0:15], v[124:127], v[152:155], v[0:15]
	s_waitcnt vmcnt(2) lgkmcnt(0)
	s_barrier
	v_add_f32_e32 v139, v139, v160
	s_cmp_ge_u32 s4, s40
	v_mfma_f32_32x32x16_bf16 v[16:31], v[140:143], v[152:155], v[16:31]
	v_mfma_f32_32x32x16_bf16 v[0:15], v[144:147], v[156:159], v[0:15]
	v_mfma_f32_32x32x16_bf16 v[16:31], v[148:151], v[156:159], v[16:31]
	v_mfma_f32_32x32x16_bf16 v[80:95], v[120:123], v[116:119], v[80:95]
	s_cbranch_scc1 .LBB0_743
	s_min_u32 s4, s17, s40
	s_mul_hi_u32 s5, s4, 0x55555556
	s_mul_i32 s5, s5, 3
	s_sub_i32 s5, s4, s5
	s_mul_i32 s6, s5, 0x3000
	s_mul_i32 s4, s4, 0x50000
	s_mov_b32 s5, s81
	v_lshl_add_u64 v[48:49], v[128:129], 0, s[4:5]
	v_lshl_add_u64 v[48:49], v[48:49], 0, s[90:91]
	s_add_i32 m0, s93, s6
	s_add_i32 s4, s41, s95
	global_load_lds_dwordx4 v[48:49], off
	v_lshl_add_u64 v[48:49], v[130:131], 0, s[80:81]
	v_lshl_add_u64 v[48:49], v[48:49], 0, s[0:1]
	s_add_i32 m0, s4, 0x1000
	s_cmp_le_u32 s19, s39
	global_load_lds_dwordx4 v[48:49], off
	s_cbranch_scc1 .LBB0_751
	v_subrev_u32_e32 v48, 64, v137
	v_cmp_lt_i32_e64 s[4:5], -1, v48
	v_cmp_lt_i32_e64 s[6:7], 31, v48
	v_cmp_lt_i32_e32 vcc, 0, v48
	v_cndmask_b32_e64 v96, v249, v96, s[4:5]
	v_cmp_lt_i32_e64 s[4:5], 32, v48
	v_cndmask_b32_e64 v80, v249, v80, s[6:7]
	v_cmp_lt_i32_e64 s[6:7], 1, v48
	v_cndmask_b32_e32 v97, v249, v97, vcc
	v_cmp_lt_i32_e32 vcc, 33, v48
	v_cndmask_b32_e64 v81, v249, v81, s[4:5]
	v_cmp_lt_i32_e64 s[4:5], 2, v48
	v_cndmask_b32_e64 v98, v249, v98, s[6:7]
	v_cmp_lt_i32_e64 s[6:7], 34, v48
	v_cndmask_b32_e32 v82, v249, v82, vcc
	v_cmp_lt_i32_e32 vcc, 7, v48
	v_cndmask_b32_e64 v99, v249, v99, s[4:5]
	v_cmp_lt_i32_e64 s[4:5], 39, v48
	v_cndmask_b32_e64 v83, v249, v83, s[6:7]
	v_cmp_lt_i32_e64 s[6:7], 8, v48
	v_cndmask_b32_e32 v100, v249, v100, vcc
	v_cmp_lt_i32_e32 vcc, 40, v48
	v_cndmask_b32_e64 v84, v249, v84, s[4:5]
	v_cmp_lt_i32_e64 s[4:5], 9, v48
	v_cndmask_b32_e64 v101, v249, v101, s[6:7]
	v_cmp_lt_i32_e64 s[6:7], 41, v48
	v_cndmask_b32_e32 v85, v249, v85, vcc
	v_cmp_lt_i32_e32 vcc, 10, v48
	v_cndmask_b32_e64 v102, v249, v102, s[4:5]
	v_cmp_lt_i32_e64 s[4:5], 42, v48
	v_cndmask_b32_e64 v86, v249, v86, s[6:7]
	v_cmp_lt_i32_e64 s[6:7], 15, v48
	v_cndmask_b32_e32 v103, v249, v103, vcc
	v_cmp_lt_i32_e32 vcc, 47, v48
	v_cndmask_b32_e64 v87, v249, v87, s[4:5]
	v_cmp_lt_i32_e64 s[4:5], 16, v48
	v_cndmask_b32_e64 v104, v249, v104, s[6:7]
	v_cmp_lt_i32_e64 s[6:7], 48, v48
	v_cndmask_b32_e32 v88, v249, v88, vcc
	v_cmp_lt_i32_e32 vcc, 17, v48
	v_cndmask_b32_e64 v105, v249, v105, s[4:5]
	v_cmp_lt_i32_e64 s[4:5], 49, v48
	v_cndmask_b32_e64 v89, v249, v89, s[6:7]
	v_cmp_lt_i32_e64 s[6:7], 18, v48
	v_cndmask_b32_e32 v106, v249, v106, vcc
	v_cmp_lt_i32_e32 vcc, 50, v48
	v_cndmask_b32_e64 v90, v249, v90, s[4:5]
	v_cmp_lt_i32_e64 s[4:5], 23, v48
	v_cndmask_b32_e64 v107, v249, v107, s[6:7]
	v_cmp_lt_i32_e64 s[6:7], 55, v48
	v_cndmask_b32_e32 v91, v249, v91, vcc
	v_cmp_lt_i32_e32 vcc, 24, v48
	v_cndmask_b32_e64 v108, v249, v108, s[4:5]
	v_cmp_lt_i32_e64 s[4:5], 56, v48
	v_cndmask_b32_e64 v92, v249, v92, s[6:7]
	v_cmp_lt_i32_e64 s[6:7], 25, v48
	v_cndmask_b32_e32 v109, v249, v109, vcc
	v_cmp_lt_i32_e32 vcc, 57, v48
	v_cndmask_b32_e64 v93, v249, v93, s[4:5]
	v_cmp_lt_i32_e64 s[4:5], 26, v48
	v_cndmask_b32_e64 v110, v249, v110, s[6:7]
	v_cmp_lt_i32_e64 s[6:7], 58, v48
	v_cndmask_b32_e32 v94, v249, v94, vcc
	s_nop 0
	v_cndmask_b32_e64 v111, v249, v111, s[4:5]
	s_nop 0
	v_cndmask_b32_e64 v95, v249, v95, s[6:7]
.LBB0_751:
	v_add3_u32 v48, s21, v133, v134
	ds_read_b128 v[68:71], v48
	ds_read_b128 v[124:127], v48 offset:512
	ds_read_b128 v[64:67], v48 offset:2048
	ds_read_b128 v[120:123], v48 offset:2560
	s_nop 0
	v_max3_f32 v48, v96, v80, v97
	v_max3_f32 v49, v81, v98, v82
	v_max3_f32 v48, v48, v99, v83
	v_max3_f32 v49, v49, v100, v84
	v_max3_f32 v48, v48, v101, v85
	v_max3_f32 v49, v49, v102, v86
	v_max3_f32 v48, v48, v103, v87
	v_max3_f32 v49, v49, v104, v88
	v_max3_f32 v48, v48, v105, v89
	v_max3_f32 v49, v49, v106, v90
	v_max3_f32 v48, v48, v107, v91
	v_max3_f32 v49, v49, v108, v92
	v_max3_f32 v48, v48, v109, v93
	v_max3_f32 v49, v49, v110, v94
	v_max3_f32 v48, v48, v111, v95
	v_max_f32_e32 v48, v48, v49
	v_mov_b32_e32 v49, v48
	s_nop 1
	v_permlane32_swap_b32_e32 v48, v49
	v_max_f32_e32 v48, v48, v49
	v_cmp_lt_f32_e32 vcc, s97, v48
	v_cmp_lg_f32_e64 s[4:5], s96, v48
	s_nop 1
	s_and_b64 s[6:7], vcc, s[2:3]
	s_andn2_b64 vcc, s[4:5], s[2:3]
	s_or_b64 s[6:7], s[6:7], vcc
	s_and_b64 vcc, s[6:7], exec
	s_cbranch_vccz .LBB0_742
	v_cndmask_b32_e64 v32, 0, v48, s[6:7]
	v_exp_f32_e64 v34, -v32
	s_or_b64 s[4:5], s[2:3], s[4:5]
	v_add_f32_e32 v138, v138, v32
	v_pk_add_f32 v[96:97], v[96:97], v[32:33] op_sel_hi:[1,0] neg_lo:[0,1] neg_hi:[0,1]
	v_pk_add_f32 v[80:81], v[80:81], v[32:33] op_sel_hi:[1,0] neg_lo:[0,1] neg_hi:[0,1]
	v_pk_add_f32 v[98:99], v[98:99], v[32:33] op_sel_hi:[1,0] neg_lo:[0,1] neg_hi:[0,1]
	v_pk_add_f32 v[82:83], v[82:83], v[32:33] op_sel_hi:[1,0] neg_lo:[0,1] neg_hi:[0,1]
	v_pk_add_f32 v[100:101], v[100:101], v[32:33] op_sel_hi:[1,0] neg_lo:[0,1] neg_hi:[0,1]
	v_pk_add_f32 v[84:85], v[84:85], v[32:33] op_sel_hi:[1,0] neg_lo:[0,1] neg_hi:[0,1]
	v_pk_add_f32 v[102:103], v[102:103], v[32:33] op_sel_hi:[1,0] neg_lo:[0,1] neg_hi:[0,1]
	v_pk_add_f32 v[86:87], v[86:87], v[32:33] op_sel_hi:[1,0] neg_lo:[0,1] neg_hi:[0,1]
	v_pk_add_f32 v[104:105], v[104:105], v[32:33] op_sel_hi:[1,0] neg_lo:[0,1] neg_hi:[0,1]
	v_pk_add_f32 v[88:89], v[88:89], v[32:33] op_sel_hi:[1,0] neg_lo:[0,1] neg_hi:[0,1]
	v_pk_add_f32 v[106:107], v[106:107], v[32:33] op_sel_hi:[1,0] neg_lo:[0,1] neg_hi:[0,1]
	v_pk_add_f32 v[90:91], v[90:91], v[32:33] op_sel_hi:[1,0] neg_lo:[0,1] neg_hi:[0,1]
	v_pk_add_f32 v[108:109], v[108:109], v[32:33] op_sel_hi:[1,0] neg_lo:[0,1] neg_hi:[0,1]
	v_pk_add_f32 v[92:93], v[92:93], v[32:33] op_sel_hi:[1,0] neg_lo:[0,1] neg_hi:[0,1]
	v_pk_add_f32 v[110:111], v[110:111], v[32:33] op_sel_hi:[1,0] neg_lo:[0,1] neg_hi:[0,1]
	v_pk_add_f32 v[94:95], v[94:95], v[32:33] op_sel_hi:[1,0] neg_lo:[0,1] neg_hi:[0,1]
	v_xor_b32_e32 v32, 0x80000000, v138
	s_andn2_b64 s[2:3], s[2:3], exec
	s_and_b64 s[4:5], s[4:5], exec
	v_mul_f32_e32 v139, v139, v34
	v_pk_mul_f32 v[30:31], v[30:31], v[34:35] op_sel_hi:[1,0]
	v_pk_mul_f32 v[28:29], v[28:29], v[34:35] op_sel_hi:[1,0]
	v_pk_mul_f32 v[26:27], v[26:27], v[34:35] op_sel_hi:[1,0]
	v_pk_mul_f32 v[24:25], v[24:25], v[34:35] op_sel_hi:[1,0]
	v_pk_mul_f32 v[22:23], v[22:23], v[34:35] op_sel_hi:[1,0]
	v_pk_mul_f32 v[20:21], v[20:21], v[34:35] op_sel_hi:[1,0]
	v_pk_mul_f32 v[18:19], v[18:19], v[34:35] op_sel_hi:[1,0]
	v_pk_mul_f32 v[16:17], v[16:17], v[34:35] op_sel_hi:[1,0]
	v_pk_mul_f32 v[14:15], v[14:15], v[34:35] op_sel_hi:[1,0]
	v_pk_mul_f32 v[12:13], v[12:13], v[34:35] op_sel_hi:[1,0]
	v_pk_mul_f32 v[10:11], v[10:11], v[34:35] op_sel_hi:[1,0]
	v_pk_mul_f32 v[8:9], v[8:9], v[34:35] op_sel_hi:[1,0]
	v_pk_mul_f32 v[6:7], v[6:7], v[34:35] op_sel_hi:[1,0]
	v_pk_mul_f32 v[4:5], v[4:5], v[34:35] op_sel_hi:[1,0]
	v_pk_mul_f32 v[2:3], v[2:3], v[34:35] op_sel_hi:[1,0]
	v_pk_mul_f32 v[0:1], v[0:1], v[34:35] op_sel_hi:[1,0]
	v_mov_b32_e32 v33, v32
	v_mov_b32_e32 v34, v32
	v_mov_b32_e32 v35, v32
	v_mov_b32_e32 v36, v32
	v_mov_b32_e32 v37, v32
	v_mov_b32_e32 v38, v32
	v_mov_b32_e32 v39, v32
	v_mov_b32_e32 v40, v32
	v_mov_b32_e32 v41, v32
	v_mov_b32_e32 v42, v32
	v_mov_b32_e32 v43, v32
	v_mov_b32_e32 v44, v32
	v_mov_b32_e32 v45, v32
	v_mov_b32_e32 v46, v32
	v_mov_b32_e32 v47, v32
	s_or_b64 s[2:3], s[2:3], s[4:5]
	s_branch .LBB0_742
